# v12 + LRU-B carry application: the 7 serialized ds_read_b64->lgkmcnt(0)->fmac->cndmask steps per (dir,tile) group now issue their LDS reads up front (one LDS latency per group instead of seven)
# speedup vs baseline: 1.0079x; 1.0079x over previous
; #define LAS __attribute__((address_space(3)))
; __device__ __forceinline__ unsigned pk2(float lo, float hi) { return f2bf(lo) | (f2bf(hi) << 16); }
; template <bool PHASE_B>
; __device__ __forceinline__ void lru_item(const Params& p, LAS unsigned char* lds, int ci, int ci_next, int jb, const int tid, v4u (&xvn)[3]) {
;     ...
;     for (int ks = 0; ks < 2; ++ks) { const int cb0 = 32 * ks + 8 * fq;
;         f32x4 s0 = *(const LAS f32x4*)(CB + cb0), s1 = *(const LAS f32x4*)(CB + cb0 + 4);
; #pragma unroll
;         for (int tap = 0; tap < 4; ++tap) { const v4u v = *(const LAS v4u*)(lds + LR_XR + (16 * rt + fr + tap) * 144 + cb0 * 2);
;             const f32x4 w0 = *(const LAS f32x4*)(CW + tap * 64 + cb0), w1 = *(const LAS f32x4*)(CW + tap * 64 + cb0 + 4);
;             s0 += (f32x4){bflo(v.x), bfhi(v.x), bflo(v.y), bfhi(v.y)} * w0; s1 += (f32x4){bflo(v.z), bfhi(v.z), bflo(v.w), bfhi(v.w)} * w1; }
;         v4u o; o.x = pk2(s0[0], s0[1]); o.y = pk2(s0[2], s0[3]); o.z = pk2(s1[0], s1[1]); o.w = pk2(s1[2], s1[3]);
;         af[ks] = __builtin_bit_cast(bf16x8, o); }
.LBB0_339:
	v_add_u32_e32 v1, v167, v157
	ds_read_b128 v[14:17], v165 offset:56832
	ds_read_b128 v[18:21], v165 offset:56848
	ds_read_b128 v[22:25], v1
	v_add_u32_e32 v31, v167, v166
	ds_read_b128 v[26:29], v31 offset:55808
	ds_read_b128 v[36:39], v31 offset:55824
	v_add_u32_e32 v50, 0xd800, v170
	v_add_u32_e32 v51, 0xdc00, v170
	s_waitcnt lgkmcnt(2)
	v_lshlrev_b32_e32 v40, 16, v22
	v_and_b32_e32 v41, 0xffff0000, v22
	v_lshlrev_b32_e32 v22, 16, v23
	v_and_b32_e32 v23, 0xffff0000, v23
	s_waitcnt lgkmcnt(1)
	v_pk_fma_f32 v[28:29], v[28:29], v[22:23], v[16:17]
	v_pk_fma_f32 v[26:27], v[26:27], v[40:41], v[14:15]
	v_lshlrev_b32_e32 v14, 16, v24
	v_and_b32_e32 v15, 0xffff0000, v24
	v_lshlrev_b32_e32 v16, 16, v25
	v_and_b32_e32 v17, 0xffff0000, v25
	s_waitcnt lgkmcnt(0)
	v_pk_fma_f32 v[38:39], v[38:39], v[16:17], v[20:21]
	v_pk_fma_f32 v[36:37], v[36:37], v[14:15], v[18:19]
	ds_read_b128 v[14:17], v1 offset:144
	ds_read_b128 v[18:21], v31 offset:56064
	ds_read_b128 v[22:25], v31 offset:56080
	v_add_u32_e32 v132, v173, v166
	s_and_b64 vcc, exec, s[6:7]
	s_waitcnt lgkmcnt(2)
	v_lshlrev_b32_e32 v40, 16, v14
	v_and_b32_e32 v41, 0xffff0000, v14
	v_lshlrev_b32_e32 v14, 16, v15
	v_and_b32_e32 v15, 0xffff0000, v15
	s_waitcnt lgkmcnt(1)
	v_pk_fma_f32 v[28:29], v[20:21], v[14:15], v[28:29]
	v_lshlrev_b32_e32 v14, 16, v16
	v_and_b32_e32 v15, 0xffff0000, v16
	v_lshlrev_b32_e32 v16, 16, v17
	v_and_b32_e32 v17, 0xffff0000, v17
	v_pk_fma_f32 v[26:27], v[18:19], v[40:41], v[26:27]
	s_waitcnt lgkmcnt(0)
	v_pk_fma_f32 v[38:39], v[24:25], v[16:17], v[38:39]
	v_pk_fma_f32 v[36:37], v[22:23], v[14:15], v[36:37]
	ds_read_b128 v[14:17], v1 offset:288
	ds_read_b128 v[18:21], v31 offset:56320
	ds_read_b128 v[22:25], v31 offset:56336
	s_waitcnt lgkmcnt(2)
	v_lshlrev_b32_e32 v40, 16, v14
	v_and_b32_e32 v41, 0xffff0000, v14
	v_lshlrev_b32_e32 v14, 16, v15
	v_and_b32_e32 v15, 0xffff0000, v15
	s_waitcnt lgkmcnt(1)
	v_pk_fma_f32 v[28:29], v[20:21], v[14:15], v[28:29]
	v_lshlrev_b32_e32 v14, 16, v16
	v_and_b32_e32 v15, 0xffff0000, v16
	v_lshlrev_b32_e32 v16, 16, v17
	v_and_b32_e32 v17, 0xffff0000, v17
	v_pk_fma_f32 v[26:27], v[18:19], v[40:41], v[26:27]
	s_waitcnt lgkmcnt(0)
	v_pk_fma_f32 v[36:37], v[22:23], v[14:15], v[36:37]
	v_pk_fma_f32 v[38:39], v[24:25], v[16:17], v[38:39]
	ds_read_b128 v[14:17], v1 offset:432
	ds_read_b128 v[18:21], v31 offset:56576
	ds_read_b128 v[22:25], v31 offset:56592
	s_waitcnt lgkmcnt(2)
	v_lshlrev_b32_e32 v40, 16, v14
	v_and_b32_e32 v41, 0xffff0000, v14
	v_lshlrev_b32_e32 v14, 16, v15
	v_and_b32_e32 v15, 0xffff0000, v15
	s_waitcnt lgkmcnt(1)
	v_pk_fma_f32 v[20:21], v[20:21], v[14:15], v[28:29]
	v_pk_fma_f32 v[14:15], v[18:19], v[40:41], v[26:27]
	v_lshlrev_b32_e32 v18, 16, v16
	v_bfe_u32 v1, v14, 16, 1
	v_add3_u32 v1, v14, v1, s33
	v_bfe_u32 v14, v15, 16, 1
	v_lshrrev_b32_e32 v1, 16, v1
	v_add3_u32 v14, v15, v14, s33
	v_and_or_b32 v14, v14, s11, v1
	v_and_b32_e32 v19, 0xffff0000, v16
	v_lshlrev_b32_e32 v16, 16, v17
	v_and_b32_e32 v17, 0xffff0000, v17
	s_waitcnt lgkmcnt(0)
	v_pk_fma_f32 v[24:25], v[24:25], v[16:17], v[38:39]
	v_pk_fma_f32 v[16:17], v[22:23], v[18:19], v[36:37]
	v_cvt_pk_bf16_f32 v15, v20, v21
	v_bfe_u32 v1, v16, 16, 1
	v_add3_u32 v1, v16, v1, s33
	v_bfe_u32 v16, v17, 16, 1
	v_lshrrev_b32_e32 v1, 16, v1
	v_add3_u32 v16, v17, v16, s33
	v_and_or_b32 v16, v16, s11, v1
	v_bfe_u32 v1, v24, 16, 1
	v_bfe_u32 v17, v25, 16, 1
	v_add3_u32 v1, v24, v1, s33
	v_add3_u32 v17, v25, v17, s33
	ds_read_b128 v[18:21], v31 offset:56960
	ds_read_b128 v[22:25], v31 offset:56976
	ds_read_b128 v[26:29], v198
	ds_read_b128 v[36:39], v31 offset:55936
	ds_read_b128 v[40:43], v31 offset:55952
	v_lshrrev_b32_e32 v1, 16, v1
	v_and_or_b32 v17, v17, s11, v1
	s_waitcnt lgkmcnt(2)
	v_lshlrev_b32_e32 v44, 16, v26
	v_and_b32_e32 v45, 0xffff0000, v26
	v_lshlrev_b32_e32 v26, 16, v27
	v_and_b32_e32 v27, 0xffff0000, v27
	s_waitcnt lgkmcnt(1)
	v_pk_fma_f32 v[38:39], v[38:39], v[26:27], v[20:21]
	v_pk_fma_f32 v[36:37], v[36:37], v[44:45], v[18:19]
	v_lshlrev_b32_e32 v18, 16, v28
	v_and_b32_e32 v19, 0xffff0000, v28
	v_lshlrev_b32_e32 v20, 16, v29
	v_and_b32_e32 v21, 0xffff0000, v29
	s_waitcnt lgkmcnt(0)
	v_pk_fma_f32 v[42:43], v[42:43], v[20:21], v[24:25]
	v_pk_fma_f32 v[40:41], v[40:41], v[18:19], v[22:23]
	ds_read_b128 v[18:21], v198 offset:144
	ds_read_b128 v[22:25], v31 offset:56192
	ds_read_b128 v[26:29], v31 offset:56208
	s_waitcnt lgkmcnt(2)
	v_lshlrev_b32_e32 v44, 16, v18
	v_and_b32_e32 v45, 0xffff0000, v18
	v_lshlrev_b32_e32 v18, 16, v19
	v_and_b32_e32 v19, 0xffff0000, v19
	s_waitcnt lgkmcnt(1)
	v_pk_fma_f32 v[38:39], v[24:25], v[18:19], v[38:39]
	v_lshlrev_b32_e32 v18, 16, v20
	v_and_b32_e32 v19, 0xffff0000, v20
	v_lshlrev_b32_e32 v20, 16, v21
	v_and_b32_e32 v21, 0xffff0000, v21
	v_pk_fma_f32 v[36:37], v[22:23], v[44:45], v[36:37]
	s_waitcnt lgkmcnt(0)
	v_pk_fma_f32 v[42:43], v[28:29], v[20:21], v[42:43]
	v_pk_fma_f32 v[40:41], v[26:27], v[18:19], v[40:41]
	ds_read_b128 v[18:21], v198 offset:288
	ds_read_b128 v[22:25], v31 offset:56448
	ds_read_b128 v[26:29], v31 offset:56464
	s_waitcnt lgkmcnt(2)
	v_lshlrev_b32_e32 v44, 16, v18
	v_and_b32_e32 v45, 0xffff0000, v18
	v_lshlrev_b32_e32 v18, 16, v19
	v_and_b32_e32 v19, 0xffff0000, v19
	s_waitcnt lgkmcnt(1)
	v_pk_fma_f32 v[38:39], v[24:25], v[18:19], v[38:39]
	v_lshlrev_b32_e32 v18, 16, v20
	v_and_b32_e32 v19, 0xffff0000, v20
	v_lshlrev_b32_e32 v20, 16, v21
	v_and_b32_e32 v21, 0xffff0000, v21
	v_pk_fma_f32 v[36:37], v[22:23], v[44:45], v[36:37]
	s_waitcnt lgkmcnt(0)
	v_pk_fma_f32 v[42:43], v[28:29], v[20:21], v[42:43]
	v_pk_fma_f32 v[40:41], v[26:27], v[18:19], v[40:41]
	ds_read_b128 v[18:21], v198 offset:432
	ds_read_b128 v[22:25], v31 offset:56704
	ds_read_b128 v[26:29], v31 offset:56720
	s_waitcnt lgkmcnt(2)
; #define LAS __attribute__((address_space(3)))
; __device__ __forceinline__ unsigned pk2(float lo, float hi) { return f2bf(lo) | (f2bf(hi) << 16); }
; template <bool PHASE_B>
; __device__ __forceinline__ void lru_item(const Params& p, LAS unsigned char* lds, int ci, int ci_next, int jb, const int tid, v4u (&xvn)[3]) {
;     ...
;     for (int ks = 0; ks < 2; ++ks) { const int cb0 = 32 * ks + 8 * fq;
;         f32x4 s0 = *(const LAS f32x4*)(CB + cb0), s1 = *(const LAS f32x4*)(CB + cb0 + 4);
; #pragma unroll
;         for (int tap = 0; tap < 4; ++tap) { const v4u v = *(const LAS v4u*)(lds + LR_XR + (16 * rt + fr + tap) * 144 + cb0 * 2);
;             const f32x4 w0 = *(const LAS f32x4*)(CW + tap * 64 + cb0), w1 = *(const LAS f32x4*)(CW + tap * 64 + cb0 + 4);
;             s0 += (f32x4){bflo(v.x), bfhi(v.x), bflo(v.y), bfhi(v.y)} * w0; s1 += (f32x4){bflo(v.z), bfhi(v.z), bflo(v.w), bfhi(v.w)} * w1; }
;         v4u o; o.x = pk2(s0[0], s0[1]); o.y = pk2(s0[2], s0[3]); o.z = pk2(s1[0], s1[1]); o.w = pk2(s1[2], s1[3]);
;         af[ks] = __builtin_bit_cast(bf16x8, o); }
;     float xc[4][4];
; #pragma unroll
;     for (int ct = 0; ct < 4; ++ct) { const int ch = 16 * ct + fr; float xr7[7];
; #pragma unroll
;         for (int j = 0; j < 7; ++j) xr7[j] = __builtin_bit_cast(float, (unsigned)(*(const LAS bf16*)(lds + LR_XR + (16 * rt + 4 * fq + j) * 144 + ch * 2)) << 16);
;         const float w0 = CW[ch], w1 = CW[64 + ch], w2 = CW[128 + ch], w3 = CW[192 + ch], b = CB[ch];
; #pragma unroll
;         for (int e = 0; e < 4; ++e) xc[ct][e] = b + xr7[e] * w0 + xr7[e + 1] * w1 + xr7[e + 2] * w2 + xr7[e + 3] * w3; }
	v_lshlrev_b32_e32 v44, 16, v18
	v_and_b32_e32 v45, 0xffff0000, v18
	v_lshlrev_b32_e32 v18, 16, v19
	v_and_b32_e32 v19, 0xffff0000, v19
	s_waitcnt lgkmcnt(1)
	v_pk_fma_f32 v[24:25], v[24:25], v[18:19], v[38:39]
	v_pk_fma_f32 v[18:19], v[22:23], v[44:45], v[36:37]
	v_lshlrev_b32_e32 v22, 16, v20
	v_bfe_u32 v1, v18, 16, 1
	v_add3_u32 v1, v18, v1, s33
	v_bfe_u32 v18, v19, 16, 1
	v_lshrrev_b32_e32 v1, 16, v1
	v_add3_u32 v18, v19, v18, s33
	v_and_or_b32 v18, v18, s11, v1
	v_and_b32_e32 v23, 0xffff0000, v20
	v_lshlrev_b32_e32 v20, 16, v21
	v_and_b32_e32 v21, 0xffff0000, v21
	s_waitcnt lgkmcnt(0)
	v_pk_fma_f32 v[28:29], v[28:29], v[20:21], v[42:43]
	v_pk_fma_f32 v[20:21], v[26:27], v[22:23], v[40:41]
	v_cvt_pk_bf16_f32 v19, v24, v25
	v_bfe_u32 v1, v20, 16, 1
	v_add3_u32 v1, v20, v1, s33
	v_bfe_u32 v20, v21, 16, 1
	v_lshrrev_b32_e32 v1, 16, v1
	v_add3_u32 v20, v21, v20, s33
	v_and_or_b32 v20, v20, s11, v1
	v_cvt_pk_bf16_f32 v21, v28, v29
	v_add_u32_e32 v1, v168, v169
	ds_read_u16 v22, v1
	s_waitcnt lgkmcnt(0)
	v_lshlrev_b32_e32 v23, 16, v22
	ds_read_u16 v22, v1 offset:144
	ds_read_u16 v31, v1 offset:288
	ds_read_u16 v38, v1 offset:432
	ds_read_u16 v39, v1 offset:576
	ds_read_u16 v46, v1 offset:720
	ds_read_u16 v1, v1 offset:864
	ds_read2_b32 v[24:25], v50 offset0:128 offset1:144
	ds_read2_b32 v[26:27], v50 offset0:192 offset1:208
	ds_read2_b32 v[28:29], v51 offset1:16
	ds_read2_b32 v[36:37], v51 offset0:64 offset1:80
	ds_read2_b32 v[40:41], v51 offset0:128 offset1:144
	s_waitcnt lgkmcnt(10)
	v_lshlrev_b32_e32 v45, 16, v22
	s_waitcnt lgkmcnt(8)
	v_lshlrev_b32_e32 v43, 16, v38
	s_waitcnt lgkmcnt(7)
	v_lshlrev_b32_e32 v42, 16, v39
	s_waitcnt lgkmcnt(3)
	v_mov_b32_e32 v38, v26
	v_mov_b32_e32 v39, v24
	v_mov_b32_e32 v22, v45
	v_pk_mul_f32 v[22:23], v[38:39], v[22:23]
	v_lshlrev_b32_e32 v44, 16, v31
	s_waitcnt lgkmcnt(0)
	v_add_f32_e32 v23, v23, v40
	v_add_f32_e32 v24, v22, v23
	v_pk_mul_f32 v[22:23], v[38:39], v[44:45]
	v_mov_b32_e32 v47, v28
	v_add_f32_e32 v23, v23, v40
	v_add_f32_e32 v26, v22, v23
	v_pk_mov_b32 v[22:23], v[42:43], v[44:45] op_sel:[1,0]
	s_nop 0
	v_pk_mul_f32 v[44:45], v[38:39], v[22:23]
	v_pk_mul_f32 v[38:39], v[38:39], v[42:43]
	v_add_f32_e32 v31, v45, v40
	v_lshlrev_b32_e32 v45, 16, v46
	v_mov_b32_e32 v46, v36
	v_pk_mul_f32 v[48:49], v[46:47], v[22:23]
	v_pk_mul_f32 v[22:23], v[46:47], v[42:43]
	v_add_f32_e32 v31, v44, v31
	v_lshlrev_b32_e32 v44, 16, v1
	v_add_f32_e32 v1, v23, v26
	v_add_f32_e32 v108, v22, v1
	v_pk_mov_b32 v[22:23], v[44:45], v[42:43] op_sel:[1,0]
	v_add_f32_e32 v39, v39, v40
	v_pk_mul_f32 v[22:23], v[46:47], v[22:23]
	v_add_f32_e32 v38, v38, v39
	v_add_f32_e32 v1, v23, v31
	v_add_f32_e32 v106, v22, v1
	v_pk_mul_f32 v[22:23], v[46:47], v[44:45]
	v_add_f32_e32 v39, v49, v24
	v_add_f32_e32 v1, v23, v38
	v_add_f32_e32 v101, v22, v1
	ds_read_u16 v1, v199
	v_add_f32_e32 v110, v48, v39
	s_waitcnt lgkmcnt(0)
	v_lshlrev_b32_e32 v23, 16, v1
	ds_read_u16 v1, v199 offset:144
	ds_read_u16 v22, v199 offset:288
	ds_read_u16 v24, v199 offset:432
	ds_read_u16 v26, v199 offset:576
	ds_read_u16 v28, v199 offset:720
	ds_read_u16 v31, v199 offset:864
	s_waitcnt lgkmcnt(3)
	v_lshlrev_b32_e32 v43, 16, v24
	v_mov_b32_e32 v24, v27
	v_lshlrev_b32_e32 v27, 16, v1
	s_waitcnt lgkmcnt(2)
	v_lshlrev_b32_e32 v42, 16, v26
	v_lshlrev_b32_e32 v26, 16, v22
	v_mov_b32_e32 v22, v27
	v_pk_mul_f32 v[22:23], v[24:25], v[22:23]
	s_nop 0
	v_add_f32_e32 v1, v23, v41
	v_add_f32_e32 v1, v22, v1
	v_pk_mul_f32 v[22:23], v[24:25], v[26:27]
	s_nop 0
	v_add_f32_e32 v23, v23, v41
	v_add_f32_e32 v36, v22, v23
	v_pk_mov_b32 v[22:23], v[42:43], v[26:27] op_sel:[1,0]
	s_nop 0
	v_pk_mul_f32 v[26:27], v[24:25], v[22:23]
	v_pk_mul_f32 v[24:25], v[24:25], v[42:43]
	v_add_f32_e32 v27, v27, v41
	v_add_f32_e32 v25, v25, v41
	v_add_f32_e32 v26, v26, v27
	v_add_f32_e32 v27, v24, v25
	s_waitcnt lgkmcnt(1)
	v_lshlrev_b32_e32 v25, 16, v28
	v_mov_b32_e32 v28, v37
	v_pk_mul_f32 v[64:65], v[28:29], v[22:23]
	v_pk_mul_f32 v[22:23], v[28:29], v[42:43]
	s_waitcnt lgkmcnt(0)
	v_lshlrev_b32_e32 v24, 16, v31
	v_add_f32_e32 v57, v65, v1
	v_add_f32_e32 v1, v23, v36
	v_add_f32_e32 v120, v22, v1
	v_pk_mov_b32 v[22:23], v[24:25], v[42:43] op_sel:[1,0]
	v_add_f32_e32 v122, v64, v57
	v_pk_mul_f32 v[22:23], v[28:29], v[22:23]
	s_nop 0
	v_add_f32_e32 v1, v23, v26
	v_add_f32_e32 v118, v22, v1
	v_pk_mul_f32 v[22:23], v[28:29], v[24:25]
	s_nop 0
	v_add_f32_e32 v1, v23, v27
	v_add_f32_e32 v113, v22, v1
	ds_read_u16 v1, v200
	s_waitcnt lgkmcnt(0)
	v_lshlrev_b32_e32 v23, 16, v1
	ds_read_u16 v1, v200 offset:144
	ds_read_u16 v22, v200 offset:288
	ds_read_u16 v31, v200 offset:432
	ds_read_u16 v38, v200 offset:576
	ds_read_u16 v49, v200 offset:720
	ds_read_u16 v52, v200 offset:864
	ds_read2_b32 v[24:25], v50 offset0:160 offset1:176
	ds_read2_b32 v[26:27], v50 offset0:224 offset1:240
	ds_read2_b32 v[28:29], v51 offset0:32 offset1:48
	ds_read2_b32 v[36:37], v51 offset0:96 offset1:112
	ds_read2_b32 v[40:41], v51 offset0:160 offset1:176
	s_waitcnt lgkmcnt(10)
	v_lshlrev_b32_e32 v47, 16, v1
	s_waitcnt lgkmcnt(3)
	v_mov_b32_e32 v44, v26
	v_mov_b32_e32 v45, v24
	v_lshlrev_b32_e32 v46, 16, v22
	v_mov_b32_e32 v22, v47
	v_pk_mul_f32 v[22:23], v[44:45], v[22:23]
	v_lshlrev_b32_e32 v43, 16, v31
	s_waitcnt lgkmcnt(0)
; template <bool PHASE_B>
; __device__ __forceinline__ void lru_item(const Params& p, LAS unsigned char* lds, int ci, int ci_next, int jb, const int tid, v4u (&xvn)[3]) {
;     ...
;     for (int ct = 0; ct < 4; ++ct) { const int ch = 16 * ct + fr; float xr7[7];
; #pragma unroll
;         for (int j = 0; j < 7; ++j) xr7[j] = __builtin_bit_cast(float, (unsigned)(*(const LAS bf16*)(lds + LR_XR + (16 * rt + 4 * fq + j) * 144 + ch * 2)) << 16);
;         const float w0 = CW[ch], w1 = CW[64 + ch], w2 = CW[128 + ch], w3 = CW[192 + ch], b = CB[ch];
; #pragma unroll
;         for (int e = 0; e < 4; ++e) xc[ct][e] = b + xr7[e] * w0 + xr7[e + 1] * w1 + xr7[e + 2] * w2 + xr7[e + 3] * w3; }
;     float av[2][4][4], uv[2][4][4], pA[2][4], pH[2][4];
; #pragma unroll
;     for (int dir = 0; dir < 2; ++dir) {
; #pragma unroll
;         for (int ct = 0; ct < 4; ++ct) {
;             f32x4 ga = (f32x4){0.f, 0.f, 0.f, 0.f}, gx = (f32x4){0.f, 0.f, 0.f, 0.f};
; #pragma unroll
;             for (int ks = 0; ks < 2; ++ks) {
;                 const bf16x8 wa = *(const LAS bf16x8*)(lds + LR_WG + ((dir * 2 + 0) * 64 + 16 * ct + fr) * 144 + (32 * ks + 8 * fq) * 2);
;                 const bf16x8 wx = *(const LAS bf16x8*)(lds + LR_WG + ((dir * 2 + 1) * 64 + 16 * ct + fr) * 144 + (32 * ks + 8 * fq) * 2);
;                 ga = MFMA16(af[ks], wa, ga); gx = MFMA16(af[ks], wx, gx); }
;             const int ch = 16 * ct + fr; const float bav = GC[(dir * 3 + 0) * 64 + ch], bxv = GC[(dir * 3 + 1) * 64 + ch], c8 = GC[(dir * 3 + 2) * 64 + ch];
;             float Al = 1.f, Hl = 0.f;
; #pragma unroll
;             for (int ee = 0; ee < 4; ++ee) { const int e = dir ? 3 - ee : ee;
;                 const float r = __builtin_amdgcn_rcpf(1.f + __expf(-(ga[e] + bav))), ig = __builtin_amdgcn_rcpf(1.f + __expf(-(gx[e] + bxv)));
;                 const float la = -c8 * r; const float a = __expf(la); const float u = __builtin_amdgcn_sqrtf((1.f - a) * (1.f + a)) * (ig * xc[ct][e]);
;                 av[dir][ct][e] = a; uv[dir][ct][e] = u; Hl = a * Hl + u; Al *= a; }
;             const int o = dir ? 3 - fq : fq; const bool odd = (o & 1) != 0, hi2 = (o & 2) != 0;
;             const float A1 = __shfl_xor(Al, 16), H1 = __shfl_xor(Hl, 16);
;             const float pxA = odd ? A1 : 1.f, pxH = odd ? H1 : 0.f;
;             const float gA = Al * A1, gH = odd ? (Al * H1 + Hl) : (A1 * Hl + H1);
	v_add_f32_e32 v1, v23, v40
	v_add_f32_e32 v1, v22, v1
	v_pk_mul_f32 v[22:23], v[44:45], v[46:47]
	v_lshlrev_b32_e32 v42, 16, v38
	v_add_f32_e32 v23, v23, v40
	v_add_f32_e32 v24, v22, v23
	v_pk_mov_b32 v[22:23], v[42:43], v[46:47] op_sel:[1,0]
	v_mov_b32_e32 v50, v36
	v_pk_mul_f32 v[46:47], v[44:45], v[22:23]
	v_pk_mul_f32 v[44:45], v[44:45], v[42:43]
	v_mov_b32_e32 v51, v28
	v_add_f32_e32 v31, v45, v40
	v_add_f32_e32 v26, v47, v40
	v_add_f32_e32 v31, v44, v31
	v_pk_mul_f32 v[44:45], v[50:51], v[22:23]
	v_pk_mul_f32 v[22:23], v[50:51], v[42:43]
	v_add_f32_e32 v26, v46, v26
	v_lshlrev_b32_e32 v47, 16, v49
	v_lshlrev_b32_e32 v46, 16, v52
	v_add_f32_e32 v45, v45, v1
	v_add_f32_e32 v1, v23, v24
	v_add_f32_e32 v130, v22, v1
	v_pk_mov_b32 v[22:23], v[46:47], v[42:43] op_sel:[1,0]
	s_nop 0
	v_pk_mul_f32 v[22:23], v[50:51], v[22:23]
	s_nop 0
	v_add_f32_e32 v1, v23, v26
	v_add_f32_e32 v128, v22, v1
	v_pk_mul_f32 v[22:23], v[50:51], v[46:47]
	s_nop 0
	v_add_f32_e32 v1, v23, v31
	v_add_f32_e32 v125, v22, v1
	ds_read_u16 v1, v201
	s_waitcnt lgkmcnt(0)
	v_lshlrev_b32_e32 v23, 16, v1
	ds_read_u16 v1, v201 offset:144
	ds_read_u16 v22, v201 offset:288
	ds_read_u16 v24, v201 offset:432
	ds_read_u16 v26, v201 offset:576
	ds_read_u16 v28, v201 offset:720
	ds_read_u16 v31, v201 offset:864
	s_waitcnt lgkmcnt(3)
	v_lshlrev_b32_e32 v43, 16, v24
	v_mov_b32_e32 v24, v27
	v_lshlrev_b32_e32 v27, 16, v1
	s_waitcnt lgkmcnt(2)
	v_lshlrev_b32_e32 v42, 16, v26
	v_lshlrev_b32_e32 v26, 16, v22
	v_mov_b32_e32 v22, v27
	v_pk_mul_f32 v[22:23], v[24:25], v[22:23]
	s_nop 0
	v_add_f32_e32 v1, v23, v41
	v_add_f32_e32 v1, v22, v1
	v_pk_mul_f32 v[22:23], v[24:25], v[26:27]
	s_nop 0
	v_add_f32_e32 v23, v23, v41
	v_add_f32_e32 v38, v22, v23
	v_pk_mov_b32 v[22:23], v[42:43], v[26:27] op_sel:[1,0]
	s_nop 0
	v_pk_mul_f32 v[26:27], v[24:25], v[22:23]
	v_pk_mul_f32 v[24:25], v[24:25], v[42:43]
	v_add_f32_e32 v27, v27, v41
	v_add_f32_e32 v25, v25, v41
	v_add_f32_e32 v26, v26, v27
	v_add_f32_e32 v27, v24, v25
	s_waitcnt lgkmcnt(1)
	v_lshlrev_b32_e32 v25, 16, v28
	v_mov_b32_e32 v28, v37
	v_pk_mul_f32 v[36:37], v[28:29], v[22:23]
	v_pk_mul_f32 v[22:23], v[28:29], v[42:43]
	s_waitcnt lgkmcnt(0)
	v_lshlrev_b32_e32 v24, 16, v31
	v_add_f32_e32 v37, v37, v1
	v_add_f32_e32 v1, v23, v38
	v_add_f32_e32 v31, v22, v1
	v_pk_mov_b32 v[22:23], v[24:25], v[42:43] op_sel:[1,0]
	s_nop 0
	v_pk_mul_f32 v[22:23], v[28:29], v[22:23]
	s_nop 0
	v_add_f32_e32 v1, v23, v26
	v_add_f32_e32 v136, v22, v1
	v_pk_mul_f32 v[22:23], v[28:29], v[24:25]
	s_nop 0
	v_add_f32_e32 v1, v23, v27
	v_add_f32_e32 v133, v22, v1
	ds_read_b128 v[22:25], v132 offset:18944
	ds_read_b128 v[26:29], v132 offset:28160
	s_waitcnt lgkmcnt(1)
	v_mfma_f32_16x16x32_bf16 v[22:25], v[14:17], v[22:25], 0
	s_waitcnt lgkmcnt(0)
	v_mfma_f32_16x16x32_bf16 v[40:43], v[14:17], v[26:29], 0
	ds_read_b128 v[26:29], v132 offset:19008
	ds_read_b128 v[50:53], v132 offset:28224
	ds_read_b32 v49, v174 offset:57088
	ds_read_b32 v47, v174 offset:57344
	ds_read_b32 v46, v174 offset:57600
	s_waitcnt lgkmcnt(4)
	v_mfma_f32_16x16x32_bf16 v[26:29], v[18:21], v[26:29], v[22:25]
	s_waitcnt lgkmcnt(3)
	v_mfma_f32_16x16x32_bf16 v[22:25], v[18:21], v[50:53], v[40:43]
	s_waitcnt lgkmcnt(2)
	s_nop 4
	v_add_f32_e32 v1, v26, v49
	v_mul_f32_e32 v1, 0xbfb8aa3b, v1
	v_exp_f32_e32 v1, v1
	s_nop 0
	v_add_f32_e32 v1, 1.0, v1
	v_rcp_f32_e32 v1, v1
	s_waitcnt lgkmcnt(1)
	v_add_f32_e32 v22, v22, v47
	v_mul_f32_e32 v22, 0xbfb8aa3b, v22
	v_exp_f32_e32 v22, v22
	s_waitcnt lgkmcnt(0)
	v_mul_f32_e32 v1, v1, v46
	v_mul_f32_e32 v1, 0xbfb8aa3b, v1
	v_exp_f32_e32 v38, v1
	v_add_f32_e32 v22, 1.0, v22
	v_rcp_f32_e32 v50, v22
	v_add_f32_e32 v23, v23, v47
	v_sub_f32_e32 v1, 1.0, v38
	v_add_f32_e32 v22, 1.0, v38
	v_mul_f32_e32 v1, v1, v22
	v_add_f32_e32 v22, v27, v49
	v_mul_f32_e32 v22, 0xbfb8aa3b, v22
	v_exp_f32_e32 v22, v22
	v_mul_f32_e32 v23, 0xbfb8aa3b, v23
	v_exp_f32_e32 v23, v23
	v_add_f32_e32 v24, v24, v47
	v_add_f32_e32 v22, 1.0, v22
	v_rcp_f32_e32 v22, v22
	v_add_f32_e32 v23, 1.0, v23
	v_rcp_f32_e32 v23, v23
	v_add_f32_e32 v25, v25, v47
	v_mul_f32_e32 v22, v22, v46
	v_mul_f32_e32 v22, 0xbfb8aa3b, v22
	v_exp_f32_e32 v41, v22
	v_mul_f32_e32 v24, 0xbfb8aa3b, v24
	v_mul_f32_e32 v25, 0xbfb8aa3b, v25
	v_sqrt_f32_e32 v1, v1
	v_sub_f32_e32 v22, 1.0, v41
	v_add_f32_e32 v26, 1.0, v41
	v_mul_f32_e32 v22, v22, v26
	v_add_f32_e32 v26, v28, v49
	v_mul_f32_e32 v26, 0xbfb8aa3b, v26
	v_exp_f32_e32 v26, v26
	v_sqrt_f32_e32 v40, v22
	v_mul_f32_e32 v22, v108, v23
	v_mul_f32_e32 v23, v38, v41
	v_add_f32_e32 v26, 1.0, v26
	v_rcp_f32_e32 v26, v26
	v_exp_f32_e32 v24, v24
	v_exp_f32_e32 v25, v25
	v_mul_f32_e32 v39, v110, v50
	v_mul_f32_e32 v26, v26, v46
	v_mul_f32_e32 v26, 0xbfb8aa3b, v26
	v_exp_f32_e32 v43, v26
	v_add_f32_e32 v24, 1.0, v24
	v_add_f32_e32 v25, 1.0, v25
	v_rcp_f32_e32 v24, v24
	v_sub_f32_e32 v26, 1.0, v43
	v_add_f32_e32 v27, 1.0, v43
	v_mul_f32_e32 v26, v26, v27
	v_sqrt_f32_e32 v42, v26
	v_add_f32_e32 v26, v29, v49
	v_mul_f32_e32 v26, 0xbfb8aa3b, v26
	v_exp_f32_e32 v26, v26
	v_mul_f32_e32 v23, v43, v23
	v_pk_mul_f32 v[48:49], v[38:39], v[0:1]
	v_rcp_f32_e32 v25, v25
	v_add_f32_e32 v26, 1.0, v26
	v_rcp_f32_e32 v26, v26
	v_pk_fma_f32 v[50:51], v[38:39], v[0:1], v[48:49] op_sel_hi:[1,1,0]
	v_mul_f32_e32 v24, v106, v24
	v_mul_f32_e32 v26, v26, v46
	v_mul_f32_e32 v26, 0xbfb8aa3b, v26
	v_exp_f32_e32 v47, v26
	s_nop 0
	v_mul_f32_e32 v29, v47, v23
	ds_bpermute_b32 v56, v171, v29
	v_sub_f32_e32 v26, 1.0, v47
	v_add_f32_e32 v27, 1.0, v47
	v_mul_f32_e32 v26, v26, v27
	v_sqrt_f32_e32 v46, v26
	s_waitcnt lgkmcnt(0)
	v_mul_f32_e32 v59, v29, v56
	ds_bpermute_b32 v60, v172, v59
	v_cndmask_b32_e64 v58, v56, 1.0, s[50:51]
	v_mul_f32_e32 v26, v101, v25
	s_waitcnt lgkmcnt(0)
; #define LAS __attribute__((address_space(3)))
; #define MFMA16(a, b, c) __builtin_amdgcn_mfma_f32_16x16x32_bf16(a, b, c, 0, 0, 0)
; template <bool PHASE_B>
; __device__ __forceinline__ void lru_item(const Params& p, LAS unsigned char* lds, int ci, int ci_next, int jb, const int tid, v4u (&xvn)[3]) {
;     ...
;         for (int ct = 0; ct < 4; ++ct) {
;             f32x4 ga = (f32x4){0.f, 0.f, 0.f, 0.f}, gx = (f32x4){0.f, 0.f, 0.f, 0.f};
; #pragma unroll
;             for (int ks = 0; ks < 2; ++ks) {
;                 const bf16x8 wa = *(const LAS bf16x8*)(lds + LR_WG + ((dir * 2 + 0) * 64 + 16 * ct + fr) * 144 + (32 * ks + 8 * fq) * 2);
;                 const bf16x8 wx = *(const LAS bf16x8*)(lds + LR_WG + ((dir * 2 + 1) * 64 + 16 * ct + fr) * 144 + (32 * ks + 8 * fq) * 2);
;                 ga = MFMA16(af[ks], wa, ga); gx = MFMA16(af[ks], wx, gx); }
;             const int ch = 16 * ct + fr; const float bav = GC[(dir * 3 + 0) * 64 + ch], bxv = GC[(dir * 3 + 1) * 64 + ch], c8 = GC[(dir * 3 + 2) * 64 + ch];
;             float Al = 1.f, Hl = 0.f;
; #pragma unroll
;             for (int ee = 0; ee < 4; ++ee) { const int e = dir ? 3 - ee : ee;
;                 const float r = __builtin_amdgcn_rcpf(1.f + __expf(-(ga[e] + bav))), ig = __builtin_amdgcn_rcpf(1.f + __expf(-(gx[e] + bxv)));
;                 const float la = -c8 * r; const float a = __expf(la); const float u = __builtin_amdgcn_sqrtf((1.f - a) * (1.f + a)) * (ig * xc[ct][e]);
;                 av[dir][ct][e] = a; uv[dir][ct][e] = u; Hl = a * Hl + u; Al *= a; }
;             const int o = dir ? 3 - fq : fq; const bool odd = (o & 1) != 0, hi2 = (o & 2) != 0;
;             const float A1 = __shfl_xor(Al, 16), H1 = __shfl_xor(Hl, 16);
;             const float pxA = odd ? A1 : 1.f, pxH = odd ? H1 : 0.f;
;             const float gA = Al * A1, gH = odd ? (Al * H1 + Hl) : (A1 * Hl + H1);
;             const float A2 = __shfl_xor(gA, 32), H2 = __shfl_xor(gH, 32);
;             const float PA = hi2 ? pxA * A2 : pxA, PH = hi2 ? (pxA * H2 + pxH) : pxH;
;             const float TA = gA * A2, TH = hi2 ? (gA * H2 + gH) : (A2 * gH + H2);
;             pA[dir][ct] = PA; pH[dir][ct] = PH;
;             ((LAS f32x2*)(lds + LR_SEG))[(dir * 8 + rt) * 64 + ch] = (f32x2){TA, TH};
	v_mul_f32_e32 v23, v58, v60
	v_cndmask_b32_e64 v206, v23, v58, s[52:53]
	v_mov_b32_e32 v23, v51
	v_pk_mul_f32 v[50:51], v[22:23], v[40:41]
	v_mul_f32_e32 v28, v59, v60
	v_pk_fma_f32 v[22:23], v[22:23], v[40:41], v[50:51] op_sel_hi:[1,1,0]
	s_nop 0
	v_mov_b32_e32 v25, v23
	v_pk_mul_f32 v[52:53], v[24:25], v[42:43]
	s_nop 0
	v_pk_fma_f32 v[22:23], v[24:25], v[42:43], v[52:53] op_sel_hi:[1,1,0]
	s_nop 0
	v_mov_b32_e32 v27, v23
	v_pk_mul_f32 v[54:55], v[26:27], v[46:47]
	s_nop 0
	v_add_f32_e32 v1, v54, v55
	ds_bpermute_b32 v22, v171, v1
	s_waitcnt lgkmcnt(0)
	v_cndmask_b32_e64 v23, v22, 0, s[50:51]
	v_fma_f32 v24, v29, v22, v1
	v_fmac_f32_e32 v22, v1, v56
	v_cndmask_b32_e64 v1, v24, v22, s[50:51]
	ds_bpermute_b32 v22, v172, v1
	s_waitcnt lgkmcnt(0)
	v_fma_f32 v24, v58, v22, v23
	v_cndmask_b32_e64 v39, v24, v23, s[52:53]
	v_fma_f32 v23, v59, v22, v1
	v_fmac_f32_e32 v22, v1, v60
	v_cndmask_b32_e64 v29, v23, v22, s[52:53]
	ds_write_b64 v175, v[28:29] offset:58624
	ds_read_b128 v[22:25], v132 offset:21248
	ds_read_b128 v[26:29], v132 offset:30464
	s_waitcnt lgkmcnt(1)
	v_mfma_f32_16x16x32_bf16 v[22:25], v[14:17], v[22:25], 0
	s_waitcnt lgkmcnt(0)
	v_mfma_f32_16x16x32_bf16 v[58:61], v[14:17], v[26:29], 0
	ds_read_b128 v[26:29], v132 offset:21312
	ds_read_b128 v[66:69], v132 offset:30528
	ds_read_b32 v40, v174 offset:57152
	ds_read_b32 v42, v174 offset:57408
	ds_read_b32 v46, v174 offset:57664
	s_waitcnt lgkmcnt(4)
	v_mfma_f32_16x16x32_bf16 v[26:29], v[18:21], v[26:29], v[22:25]
	s_waitcnt lgkmcnt(3)
	v_mfma_f32_16x16x32_bf16 v[22:25], v[18:21], v[66:69], v[58:61]
	s_waitcnt lgkmcnt(2)
	s_nop 4
	v_add_f32_e32 v1, v26, v40
	v_mul_f32_e32 v1, 0xbfb8aa3b, v1
	v_exp_f32_e32 v1, v1
	s_nop 0
	v_add_f32_e32 v1, 1.0, v1
	v_rcp_f32_e32 v1, v1
	s_waitcnt lgkmcnt(1)
	v_add_f32_e32 v22, v22, v42
	v_mul_f32_e32 v22, 0xbfb8aa3b, v22
	v_exp_f32_e32 v22, v22
	s_waitcnt lgkmcnt(0)
	v_mul_f32_e32 v1, v1, v46
	v_mul_f32_e32 v1, 0xbfb8aa3b, v1
	v_exp_f32_e32 v56, v1
	v_add_f32_e32 v22, 1.0, v22
	v_rcp_f32_e32 v48, v22
	v_add_f32_e32 v23, v23, v42
	v_sub_f32_e32 v1, 1.0, v56
	v_add_f32_e32 v22, 1.0, v56
	v_mul_f32_e32 v1, v1, v22
	v_add_f32_e32 v22, v27, v40
	v_mul_f32_e32 v22, 0xbfb8aa3b, v22
	v_exp_f32_e32 v22, v22
	v_mul_f32_e32 v23, 0xbfb8aa3b, v23
	v_exp_f32_e32 v23, v23
	v_add_f32_e32 v24, v24, v42
	v_add_f32_e32 v22, 1.0, v22
	v_rcp_f32_e32 v22, v22
	v_add_f32_e32 v23, 1.0, v23
	v_rcp_f32_e32 v23, v23
	v_add_f32_e32 v25, v25, v42
	v_mul_f32_e32 v22, v22, v46
	v_mul_f32_e32 v22, 0xbfb8aa3b, v22
	v_exp_f32_e32 v59, v22
	v_mul_f32_e32 v24, 0xbfb8aa3b, v24
	v_mul_f32_e32 v25, 0xbfb8aa3b, v25
	v_sqrt_f32_e32 v1, v1
	v_sub_f32_e32 v22, 1.0, v59
	v_add_f32_e32 v26, 1.0, v59
	v_mul_f32_e32 v22, v22, v26
	v_add_f32_e32 v26, v28, v40
	v_mul_f32_e32 v26, 0xbfb8aa3b, v26
	v_exp_f32_e32 v26, v26
	v_sqrt_f32_e32 v58, v22
	v_mul_f32_e32 v22, v120, v23
	v_mul_f32_e32 v23, v56, v59
	v_add_f32_e32 v26, 1.0, v26
	v_rcp_f32_e32 v26, v26
	v_exp_f32_e32 v24, v24
	v_exp_f32_e32 v25, v25
	v_mul_f32_e32 v57, v122, v48
	v_mul_f32_e32 v26, v26, v46
	v_mul_f32_e32 v26, 0xbfb8aa3b, v26
	v_exp_f32_e32 v61, v26
	v_add_f32_e32 v24, 1.0, v24
	v_add_f32_e32 v25, 1.0, v25
	v_pk_mul_f32 v[64:65], v[56:57], v[0:1]
	v_sub_f32_e32 v26, 1.0, v61
	v_add_f32_e32 v27, 1.0, v61
	v_mul_f32_e32 v26, v26, v27
	v_sqrt_f32_e32 v60, v26
	v_add_f32_e32 v26, v29, v40
	v_mul_f32_e32 v26, 0xbfb8aa3b, v26
	v_exp_f32_e32 v26, v26
	v_mul_f32_e32 v23, v61, v23
	v_rcp_f32_e32 v24, v24
	v_rcp_f32_e32 v25, v25
	v_add_f32_e32 v26, 1.0, v26
	v_rcp_f32_e32 v26, v26
	v_pk_fma_f32 v[66:67], v[56:57], v[0:1], v[64:65] op_sel_hi:[1,1,0]
	v_mul_f32_e32 v24, v118, v24
	v_mul_f32_e32 v26, v26, v46
	v_mul_f32_e32 v26, 0xbfb8aa3b, v26
	v_exp_f32_e32 v63, v26
	s_nop 0
	v_mul_f32_e32 v29, v63, v23
	ds_bpermute_b32 v42, v171, v29
	v_sub_f32_e32 v26, 1.0, v63
	v_add_f32_e32 v27, 1.0, v63
	v_mul_f32_e32 v26, v26, v27
	v_sqrt_f32_e32 v62, v26
	s_waitcnt lgkmcnt(0)
	v_mul_f32_e32 v51, v29, v42
	ds_bpermute_b32 v53, v172, v51
	v_cndmask_b32_e64 v46, v42, 1.0, s[50:51]
	v_mul_f32_e32 v26, v113, v25
	s_waitcnt lgkmcnt(0)
	v_mul_f32_e32 v23, v46, v53
	v_cndmask_b32_e64 v40, v23, v46, s[52:53]
	v_mov_b32_e32 v23, v67
	v_pk_mul_f32 v[66:67], v[22:23], v[58:59]
	v_mul_f32_e32 v28, v51, v53
	v_pk_fma_f32 v[22:23], v[22:23], v[58:59], v[66:67] op_sel_hi:[1,1,0]
	s_nop 0
	v_mov_b32_e32 v25, v23
	v_pk_mul_f32 v[68:69], v[24:25], v[60:61]
	s_nop 0
	v_pk_fma_f32 v[22:23], v[24:25], v[60:61], v[68:69] op_sel_hi:[1,1,0]
	v_add_f32_e32 v69, v44, v45
	v_mov_b32_e32 v27, v23
	v_pk_mul_f32 v[70:71], v[26:27], v[62:63]
	s_nop 0
	v_add_f32_e32 v1, v70, v71
	ds_bpermute_b32 v22, v171, v1
	v_add_f32_e32 v71, v36, v37
	s_waitcnt lgkmcnt(0)
	v_cndmask_b32_e64 v23, v22, 0, s[50:51]
	v_fma_f32 v24, v29, v22, v1
	v_fmac_f32_e32 v22, v1, v42
	v_cndmask_b32_e64 v1, v24, v22, s[50:51]
	ds_bpermute_b32 v22, v172, v1
	s_waitcnt lgkmcnt(0)
	v_fma_f32 v24, v46, v22, v23
	v_cndmask_b32_e64 v42, v24, v23, s[52:53]
	v_fma_f32 v23, v51, v22, v1
	v_fmac_f32_e32 v22, v1, v53
	v_cndmask_b32_e64 v29, v23, v22, s[52:53]
	ds_write_b64 v175, v[28:29] offset:58752
	ds_read_b128 v[22:25], v132 offset:23552
	ds_read_b128 v[26:29], v132 offset:32768
	s_waitcnt lgkmcnt(1)
	v_mfma_f32_16x16x32_bf16 v[22:25], v[14:17], v[22:25], 0
	ds_read_b128 v[72:75], v132 offset:23616
	ds_read_b128 v[76:79], v132 offset:32832
	s_waitcnt lgkmcnt(2)
	v_mfma_f32_16x16x32_bf16 v[26:29], v[14:17], v[26:29], 0
	s_waitcnt lgkmcnt(1)
	v_mfma_f32_16x16x32_bf16 v[80:83], v[18:21], v[72:75], v[22:25]
	s_waitcnt lgkmcnt(0)
; #define LAS __attribute__((address_space(3)))
; #define MFMA16(a, b, c) __builtin_amdgcn_mfma_f32_16x16x32_bf16(a, b, c, 0, 0, 0)
; template <bool PHASE_B>
; __device__ __forceinline__ void lru_item(const Params& p, LAS unsigned char* lds, int ci, int ci_next, int jb, const int tid, v4u (&xvn)[3]) {
;     ...
;         for (int ct = 0; ct < 4; ++ct) {
;             f32x4 ga = (f32x4){0.f, 0.f, 0.f, 0.f}, gx = (f32x4){0.f, 0.f, 0.f, 0.f};
; #pragma unroll
;             for (int ks = 0; ks < 2; ++ks) {
;                 const bf16x8 wa = *(const LAS bf16x8*)(lds + LR_WG + ((dir * 2 + 0) * 64 + 16 * ct + fr) * 144 + (32 * ks + 8 * fq) * 2);
;                 const bf16x8 wx = *(const LAS bf16x8*)(lds + LR_WG + ((dir * 2 + 1) * 64 + 16 * ct + fr) * 144 + (32 * ks + 8 * fq) * 2);
;                 ga = MFMA16(af[ks], wa, ga); gx = MFMA16(af[ks], wx, gx); }
;             const int ch = 16 * ct + fr; const float bav = GC[(dir * 3 + 0) * 64 + ch], bxv = GC[(dir * 3 + 1) * 64 + ch], c8 = GC[(dir * 3 + 2) * 64 + ch];
;             float Al = 1.f, Hl = 0.f;
; #pragma unroll
;             for (int ee = 0; ee < 4; ++ee) { const int e = dir ? 3 - ee : ee;
;                 const float r = __builtin_amdgcn_rcpf(1.f + __expf(-(ga[e] + bav))), ig = __builtin_amdgcn_rcpf(1.f + __expf(-(gx[e] + bxv)));
;                 const float la = -c8 * r; const float a = __expf(la); const float u = __builtin_amdgcn_sqrtf((1.f - a) * (1.f + a)) * (ig * xc[ct][e]);
;                 av[dir][ct][e] = a; uv[dir][ct][e] = u; Hl = a * Hl + u; Al *= a; }
;             const int o = dir ? 3 - fq : fq; const bool odd = (o & 1) != 0, hi2 = (o & 2) != 0;
;             const float A1 = __shfl_xor(Al, 16), H1 = __shfl_xor(Hl, 16);
;             const float pxA = odd ? A1 : 1.f, pxH = odd ? H1 : 0.f;
;             const float gA = Al * A1, gH = odd ? (Al * H1 + Hl) : (A1 * Hl + H1);
;             const float A2 = __shfl_xor(gA, 32), H2 = __shfl_xor(gH, 32);
;             const float PA = hi2 ? pxA * A2 : pxA, PH = hi2 ? (pxA * H2 + pxH) : pxH;
;             const float TA = gA * A2, TH = hi2 ? (gA * H2 + gH) : (A2 * gH + H2);
;             pA[dir][ct] = PA; pH[dir][ct] = PH;
;             ((LAS f32x2*)(lds + LR_SEG))[(dir * 8 + rt) * 64 + ch] = (f32x2){TA, TH};
	v_mfma_f32_16x16x32_bf16 v[22:25], v[18:21], v[76:79], v[26:29]
	s_nop 3
	ds_read_b32 v26, v174 offset:57216
	ds_read_b32 v27, v174 offset:57472
	ds_read_b32 v28, v174 offset:57728
	s_waitcnt lgkmcnt(2)
	v_add_f32_e32 v1, v80, v26
	v_mul_f32_e32 v1, 0xbfb8aa3b, v1
	v_exp_f32_e32 v1, v1
	s_waitcnt lgkmcnt(1)
	v_add_f32_e32 v22, v22, v27
	v_mul_f32_e32 v22, 0xbfb8aa3b, v22
	v_exp_f32_e32 v22, v22
	v_add_f32_e32 v1, 1.0, v1
	v_rcp_f32_e32 v1, v1
	v_add_f32_e32 v23, v23, v27
	v_add_f32_e32 v22, 1.0, v22
	v_rcp_f32_e32 v29, v22
	s_waitcnt lgkmcnt(0)
	v_mul_f32_e32 v1, v1, v28
	v_mul_f32_e32 v1, 0xbfb8aa3b, v1
	v_exp_f32_e32 v72, v1
	v_mul_f32_e32 v23, 0xbfb8aa3b, v23
	v_exp_f32_e32 v23, v23
	v_add_f32_e32 v24, v24, v27
	v_sub_f32_e32 v1, 1.0, v72
	v_add_f32_e32 v22, 1.0, v72
	v_mul_f32_e32 v1, v1, v22
	v_add_f32_e32 v22, v81, v26
	v_mul_f32_e32 v22, 0xbfb8aa3b, v22
	v_exp_f32_e32 v22, v22
	v_add_f32_e32 v23, 1.0, v23
	v_rcp_f32_e32 v23, v23
	v_add_f32_e32 v25, v25, v27
	v_add_f32_e32 v22, 1.0, v22
	v_rcp_f32_e32 v22, v22
	v_mul_f32_e32 v24, 0xbfb8aa3b, v24
	v_mul_f32_e32 v25, 0xbfb8aa3b, v25
	v_sqrt_f32_e32 v1, v1
	v_mul_f32_e32 v22, v22, v28
	v_mul_f32_e32 v22, 0xbfb8aa3b, v22
	v_exp_f32_e32 v75, v22
	v_exp_f32_e32 v24, v24
	v_exp_f32_e32 v25, v25
	v_mul_f32_e32 v73, v69, v29
	v_sub_f32_e32 v22, 1.0, v75
	v_add_f32_e32 v46, 1.0, v75
	v_mul_f32_e32 v22, v22, v46
	v_add_f32_e32 v46, v82, v26
	v_mul_f32_e32 v46, 0xbfb8aa3b, v46
	v_add_f32_e32 v26, v83, v26
	v_exp_f32_e32 v46, v46
	v_mul_f32_e32 v26, 0xbfb8aa3b, v26
	v_exp_f32_e32 v26, v26
	v_sqrt_f32_e32 v74, v22
	v_add_f32_e32 v46, 1.0, v46
	v_rcp_f32_e32 v46, v46
	v_add_f32_e32 v26, 1.0, v26
	v_rcp_f32_e32 v26, v26
	v_mul_f32_e32 v22, v130, v23
	v_mul_f32_e32 v46, v46, v28
	v_mul_f32_e32 v46, 0xbfb8aa3b, v46
	v_mul_f32_e32 v26, v26, v28
	v_exp_f32_e32 v77, v46
	v_mul_f32_e32 v26, 0xbfb8aa3b, v26
	v_exp_f32_e32 v79, v26
	v_mul_f32_e32 v23, v72, v75
	v_sub_f32_e32 v46, 1.0, v77
	v_add_f32_e32 v48, 1.0, v77
	v_mul_f32_e32 v23, v77, v23
	v_mul_f32_e32 v46, v46, v48
	v_mul_f32_e32 v48, v79, v23
	ds_bpermute_b32 v51, v171, v48
	v_add_f32_e32 v24, 1.0, v24
	v_add_f32_e32 v25, 1.0, v25
	v_pk_mul_f32 v[44:45], v[72:73], v[0:1]
	v_rcp_f32_e32 v24, v24
	s_waitcnt lgkmcnt(0)
	v_mul_f32_e32 v55, v48, v51
	ds_bpermute_b32 v57, v172, v55
	v_cndmask_b32_e64 v53, v51, 1.0, s[50:51]
	v_rcp_f32_e32 v25, v25
	v_pk_fma_f32 v[80:81], v[72:73], v[0:1], v[44:45] op_sel_hi:[1,1,0]
	v_sqrt_f32_e32 v76, v46
	s_waitcnt lgkmcnt(0)
	v_mul_f32_e32 v23, v53, v57
	v_cndmask_b32_e64 v46, v23, v53, s[52:53]
	v_mov_b32_e32 v23, v81
	v_sub_f32_e32 v26, 1.0, v79
	v_add_f32_e32 v27, 1.0, v79
	v_pk_mul_f32 v[80:81], v[22:23], v[74:75]
	v_mul_f32_e32 v26, v26, v27
	v_pk_fma_f32 v[22:23], v[22:23], v[74:75], v[80:81] op_sel_hi:[1,1,0]
	v_mul_f32_e32 v24, v128, v24
	v_sqrt_f32_e32 v78, v26
	v_mul_f32_e32 v26, v125, v25
	v_mov_b32_e32 v25, v23
	v_pk_mul_f32 v[82:83], v[24:25], v[76:77]
	v_mul_f32_e32 v28, v55, v57
	v_pk_fma_f32 v[22:23], v[24:25], v[76:77], v[82:83] op_sel_hi:[1,1,0]
	s_nop 0
	v_mov_b32_e32 v27, v23
	v_pk_mul_f32 v[84:85], v[26:27], v[78:79]
	s_nop 0
	v_add_f32_e32 v1, v84, v85
	ds_bpermute_b32 v22, v171, v1
	s_waitcnt lgkmcnt(0)
	v_cndmask_b32_e64 v23, v22, 0, s[50:51]
	v_fma_f32 v24, v48, v22, v1
	v_fmac_f32_e32 v22, v1, v51
	v_cndmask_b32_e64 v1, v24, v22, s[50:51]
	ds_bpermute_b32 v22, v172, v1
	s_waitcnt lgkmcnt(0)
	v_fma_f32 v24, v53, v22, v23
	v_cndmask_b32_e64 v44, v24, v23, s[52:53]
	v_fma_f32 v23, v55, v22, v1
	v_fmac_f32_e32 v22, v1, v57
	v_cndmask_b32_e64 v29, v23, v22, s[52:53]
	ds_write_b64 v175, v[28:29] offset:58880
	ds_read_b128 v[22:25], v132 offset:25856
	ds_read_b128 v[26:29], v132 offset:35072
	s_waitcnt lgkmcnt(1)
	v_mfma_f32_16x16x32_bf16 v[22:25], v[14:17], v[22:25], 0
	ds_read_b128 v[86:89], v132 offset:25920
	ds_read_b128 v[90:93], v132 offset:35136
	s_waitcnt lgkmcnt(2)
	v_mfma_f32_16x16x32_bf16 v[26:29], v[14:17], v[26:29], 0
	s_waitcnt lgkmcnt(1)
	v_mfma_f32_16x16x32_bf16 v[94:97], v[18:21], v[86:89], v[22:25]
	s_waitcnt lgkmcnt(0)
	v_mfma_f32_16x16x32_bf16 v[22:25], v[18:21], v[90:93], v[26:29]
	s_nop 3
	ds_read_b32 v26, v174 offset:57280
	ds_read_b32 v27, v174 offset:57536
	ds_read_b32 v28, v174 offset:57792
	s_waitcnt lgkmcnt(2)
	v_add_f32_e32 v1, v94, v26
	v_mul_f32_e32 v1, 0xbfb8aa3b, v1
	v_exp_f32_e32 v1, v1
	s_waitcnt lgkmcnt(1)
	v_add_f32_e32 v22, v22, v27
	v_mul_f32_e32 v22, 0xbfb8aa3b, v22
	v_exp_f32_e32 v22, v22
	v_add_f32_e32 v1, 1.0, v1
	v_rcp_f32_e32 v1, v1
	v_add_f32_e32 v23, v23, v27
	v_add_f32_e32 v22, 1.0, v22
	v_rcp_f32_e32 v29, v22
	s_waitcnt lgkmcnt(0)
	v_mul_f32_e32 v1, v1, v28
	v_mul_f32_e32 v1, 0xbfb8aa3b, v1
	v_exp_f32_e32 v86, v1
	v_mul_f32_e32 v23, 0xbfb8aa3b, v23
	v_exp_f32_e32 v23, v23
	v_add_f32_e32 v24, v24, v27
	v_sub_f32_e32 v1, 1.0, v86
	v_add_f32_e32 v22, 1.0, v86
	v_mul_f32_e32 v1, v1, v22
	v_add_f32_e32 v22, v95, v26
	v_mul_f32_e32 v22, 0xbfb8aa3b, v22
	v_exp_f32_e32 v22, v22
	v_add_f32_e32 v23, 1.0, v23
	v_rcp_f32_e32 v23, v23
	v_add_f32_e32 v25, v25, v27
	v_add_f32_e32 v22, 1.0, v22
	v_rcp_f32_e32 v22, v22
	v_mul_f32_e32 v24, 0xbfb8aa3b, v24
	v_mul_f32_e32 v25, 0xbfb8aa3b, v25
	v_sqrt_f32_e32 v1, v1
	v_mul_f32_e32 v22, v22, v28
	v_mul_f32_e32 v22, 0xbfb8aa3b, v22
	v_exp_f32_e32 v89, v22
	v_exp_f32_e32 v24, v24
	v_exp_f32_e32 v25, v25
	v_mul_f32_e32 v87, v71, v29
	v_sub_f32_e32 v22, 1.0, v89
	v_add_f32_e32 v48, 1.0, v89
	v_mul_f32_e32 v22, v22, v48
	v_add_f32_e32 v48, v96, v26
	v_mul_f32_e32 v48, 0xbfb8aa3b, v48
	v_add_f32_e32 v26, v97, v26
	v_exp_f32_e32 v48, v48
	v_mul_f32_e32 v26, 0xbfb8aa3b, v26
	v_exp_f32_e32 v26, v26
	v_sqrt_f32_e32 v88, v22
	v_add_f32_e32 v48, 1.0, v48
	v_rcp_f32_e32 v48, v48
	v_add_f32_e32 v26, 1.0, v26
	v_rcp_f32_e32 v26, v26
	v_mul_f32_e32 v22, v31, v23
	v_mul_f32_e32 v48, v48, v28
	v_mul_f32_e32 v48, 0xbfb8aa3b, v48
	v_mul_f32_e32 v26, v26, v28
	v_exp_f32_e32 v91, v48
	v_mul_f32_e32 v26, 0xbfb8aa3b, v26
	v_exp_f32_e32 v93, v26
	v_mul_f32_e32 v23, v86, v89
	v_sub_f32_e32 v48, 1.0, v91
	v_add_f32_e32 v51, 1.0, v91
	v_mul_f32_e32 v23, v91, v23
	v_mul_f32_e32 v48, v48, v51
	v_mul_f32_e32 v51, v93, v23
	ds_bpermute_b32 v53, v171, v51
	v_add_f32_e32 v24, 1.0, v24
	v_add_f32_e32 v25, 1.0, v25
	v_pk_mul_f32 v[36:37], v[86:87], v[0:1]
	v_rcp_f32_e32 v24, v24
	s_waitcnt lgkmcnt(0)
; #define LAS __attribute__((address_space(3)))
; #define MFMA16(a, b, c) __builtin_amdgcn_mfma_f32_16x16x32_bf16(a, b, c, 0, 0, 0)
; template <bool PHASE_B>
; __device__ __forceinline__ void lru_item(const Params& p, LAS unsigned char* lds, int ci, int ci_next, int jb, const int tid, v4u (&xvn)[3]) {
;     ...
;         for (int ct = 0; ct < 4; ++ct) {
;             f32x4 ga = (f32x4){0.f, 0.f, 0.f, 0.f}, gx = (f32x4){0.f, 0.f, 0.f, 0.f};
; #pragma unroll
;             for (int ks = 0; ks < 2; ++ks) {
;                 const bf16x8 wa = *(const LAS bf16x8*)(lds + LR_WG + ((dir * 2 + 0) * 64 + 16 * ct + fr) * 144 + (32 * ks + 8 * fq) * 2);
;                 const bf16x8 wx = *(const LAS bf16x8*)(lds + LR_WG + ((dir * 2 + 1) * 64 + 16 * ct + fr) * 144 + (32 * ks + 8 * fq) * 2);
;                 ga = MFMA16(af[ks], wa, ga); gx = MFMA16(af[ks], wx, gx); }
;             const int ch = 16 * ct + fr; const float bav = GC[(dir * 3 + 0) * 64 + ch], bxv = GC[(dir * 3 + 1) * 64 + ch], c8 = GC[(dir * 3 + 2) * 64 + ch];
;             float Al = 1.f, Hl = 0.f;
; #pragma unroll
;             for (int ee = 0; ee < 4; ++ee) { const int e = dir ? 3 - ee : ee;
;                 const float r = __builtin_amdgcn_rcpf(1.f + __expf(-(ga[e] + bav))), ig = __builtin_amdgcn_rcpf(1.f + __expf(-(gx[e] + bxv)));
;                 const float la = -c8 * r; const float a = __expf(la); const float u = __builtin_amdgcn_sqrtf((1.f - a) * (1.f + a)) * (ig * xc[ct][e]);
;                 av[dir][ct][e] = a; uv[dir][ct][e] = u; Hl = a * Hl + u; Al *= a; }
;             const int o = dir ? 3 - fq : fq; const bool odd = (o & 1) != 0, hi2 = (o & 2) != 0;
;             const float A1 = __shfl_xor(Al, 16), H1 = __shfl_xor(Hl, 16);
;             const float pxA = odd ? A1 : 1.f, pxH = odd ? H1 : 0.f;
;             const float gA = Al * A1, gH = odd ? (Al * H1 + Hl) : (A1 * Hl + H1);
;             const float A2 = __shfl_xor(gA, 32), H2 = __shfl_xor(gH, 32);
;             const float PA = hi2 ? pxA * A2 : pxA, PH = hi2 ? (pxA * H2 + pxH) : pxH;
;             const float TA = gA * A2, TH = hi2 ? (gA * H2 + gH) : (A2 * gH + H2);
;             pA[dir][ct] = PA; pH[dir][ct] = PH;
;             ((LAS f32x2*)(lds + LR_SEG))[(dir * 8 + rt) * 64 + ch] = (f32x2){TA, TH};
	v_mul_f32_e32 v57, v51, v53
	ds_bpermute_b32 v58, v172, v57
	v_cndmask_b32_e64 v55, v53, 1.0, s[50:51]
	v_rcp_f32_e32 v25, v25
	v_pk_fma_f32 v[94:95], v[86:87], v[0:1], v[36:37] op_sel_hi:[1,1,0]
	v_sqrt_f32_e32 v90, v48
	s_waitcnt lgkmcnt(0)
	v_mul_f32_e32 v23, v55, v58
	v_cndmask_b32_e64 v48, v23, v55, s[52:53]
	v_mov_b32_e32 v23, v95
	v_sub_f32_e32 v26, 1.0, v93
	v_add_f32_e32 v27, 1.0, v93
	v_pk_mul_f32 v[94:95], v[22:23], v[88:89]
	v_mul_f32_e32 v26, v26, v27
	v_pk_fma_f32 v[22:23], v[22:23], v[88:89], v[94:95] op_sel_hi:[1,1,0]
	v_mul_f32_e32 v24, v136, v24
	v_sqrt_f32_e32 v92, v26
	v_mul_f32_e32 v26, v133, v25
	v_mov_b32_e32 v25, v23
	v_pk_mul_f32 v[96:97], v[24:25], v[90:91]
	v_mul_f32_e32 v28, v57, v58
	v_pk_fma_f32 v[22:23], v[24:25], v[90:91], v[96:97] op_sel_hi:[1,1,0]
	s_nop 0
	v_mov_b32_e32 v27, v23
	v_pk_mul_f32 v[98:99], v[26:27], v[92:93]
	s_nop 0
	v_add_f32_e32 v1, v98, v99
	ds_bpermute_b32 v22, v171, v1
	s_waitcnt lgkmcnt(0)
	v_cndmask_b32_e64 v23, v22, 0, s[50:51]
	v_fma_f32 v24, v51, v22, v1
	v_fmac_f32_e32 v22, v1, v53
	v_cndmask_b32_e64 v1, v24, v22, s[50:51]
	ds_bpermute_b32 v22, v172, v1
	s_waitcnt lgkmcnt(0)
	v_fma_f32 v24, v55, v22, v23
	v_cndmask_b32_e64 v36, v24, v23, s[52:53]
	v_fma_f32 v23, v57, v22, v1
	v_fmac_f32_e32 v22, v1, v58
	v_cndmask_b32_e64 v29, v23, v22, s[52:53]
	ds_write_b64 v175, v[28:29] offset:59008
	ds_read_b128 v[22:25], v132 offset:37376
	ds_read_b128 v[26:29], v132 offset:46592
	s_waitcnt lgkmcnt(1)
	v_mfma_f32_16x16x32_bf16 v[22:25], v[14:17], v[22:25], 0
	s_waitcnt lgkmcnt(0)
	v_mfma_f32_16x16x32_bf16 v[102:105], v[14:17], v[26:29], 0
	ds_read_b128 v[26:29], v132 offset:37440
	ds_read_b128 v[114:117], v132 offset:46656
	ds_read_b32 v55, v174 offset:57856
	ds_read_b32 v57, v174 offset:58112
	ds_read_b32 v58, v174 offset:58368
	s_waitcnt lgkmcnt(4)
	v_mfma_f32_16x16x32_bf16 v[26:29], v[18:21], v[26:29], v[22:25]
	s_waitcnt lgkmcnt(3)
	v_mfma_f32_16x16x32_bf16 v[22:25], v[18:21], v[114:117], v[102:105]
	s_waitcnt lgkmcnt(2)
	s_nop 4
	v_add_f32_e32 v1, v29, v55
	v_mul_f32_e32 v1, 0xbfb8aa3b, v1
	v_exp_f32_e32 v1, v1
	s_nop 0
	v_add_f32_e32 v1, 1.0, v1
	v_rcp_f32_e32 v1, v1
	s_waitcnt lgkmcnt(1)
	v_add_f32_e32 v25, v25, v57
	v_mul_f32_e32 v25, 0xbfb8aa3b, v25
	v_exp_f32_e32 v25, v25
	s_waitcnt lgkmcnt(0)
	v_mul_f32_e32 v1, v1, v58
	v_mul_f32_e32 v1, 0xbfb8aa3b, v1
	v_exp_f32_e32 v100, v1
	v_add_f32_e32 v25, 1.0, v25
	v_rcp_f32_e32 v25, v25
	v_add_f32_e32 v23, v23, v57
	v_sub_f32_e32 v1, 1.0, v100
	v_add_f32_e32 v29, 1.0, v100
	v_mul_f32_e32 v1, v1, v29
	v_sqrt_f32_e32 v1, v1
	v_mul_f32_e32 v101, v101, v25
	v_mul_f32_e32 v23, 0xbfb8aa3b, v23
	v_exp_f32_e32 v23, v23
	v_pk_mul_f32 v[102:103], v[100:101], v[0:1]
	v_add_f32_e32 v24, v24, v57
	v_pk_fma_f32 v[114:115], v[100:101], v[0:1], v[102:103] op_sel_hi:[1,1,0]
	v_add_f32_e32 v1, v28, v55
	v_mul_f32_e32 v1, 0xbfb8aa3b, v1
	v_exp_f32_e32 v1, v1
	v_add_f32_e32 v23, 1.0, v23
	v_rcp_f32_e32 v23, v23
	v_mul_f32_e32 v24, 0xbfb8aa3b, v24
	v_add_f32_e32 v1, 1.0, v1
	v_rcp_f32_e32 v1, v1
	v_mul_f32_e32 v23, v108, v23
	v_exp_f32_e32 v24, v24
	v_add_f32_e32 v22, v22, v57
	v_mul_f32_e32 v1, v1, v58
	v_mul_f32_e32 v1, 0xbfb8aa3b, v1
	v_exp_f32_e32 v105, v1
	v_mul_f32_e32 v22, 0xbfb8aa3b, v22
	v_add_f32_e32 v24, 1.0, v24
	v_exp_f32_e32 v22, v22
	v_sub_f32_e32 v1, 1.0, v105
	v_add_f32_e32 v25, 1.0, v105
	v_mul_f32_e32 v1, v1, v25
	v_add_f32_e32 v25, v27, v55
	v_mul_f32_e32 v25, 0xbfb8aa3b, v25
	v_exp_f32_e32 v25, v25
	v_rcp_f32_e32 v24, v24
	v_sqrt_f32_e32 v104, v1
	v_add_f32_e32 v22, 1.0, v22
	v_add_f32_e32 v25, 1.0, v25
	v_rcp_f32_e32 v25, v25
	v_mul_f32_e32 v114, v106, v24
	v_rcp_f32_e32 v22, v22
	v_pk_mul_f32 v[106:107], v[114:115], v[104:105]
	v_mul_f32_e32 v25, v25, v58
	v_mul_f32_e32 v25, 0xbfb8aa3b, v25
	v_exp_f32_e32 v51, v25
	v_add_f32_e32 v1, v106, v107
	v_mul_f32_e32 v24, v100, v105
	v_mul_f32_e32 v22, v110, v22
	v_sub_f32_e32 v25, 1.0, v51
	v_add_f32_e32 v27, 1.0, v51
	v_mul_f32_e32 v25, v25, v27
	v_sqrt_f32_e32 v25, v25
	v_mul_f32_e32 v1, v51, v1
	v_mul_f32_e32 v24, v51, v24
	v_mul_f32_e32 v53, v23, v25
	v_add_f32_e32 v23, v26, v55
	v_mul_f32_e32 v23, 0xbfb8aa3b, v23
	v_exp_f32_e32 v23, v23
	s_nop 0
	v_add_f32_e32 v23, 1.0, v23
	v_rcp_f32_e32 v23, v23
	s_nop 0
	v_mul_f32_e32 v23, v23, v58
	v_mul_f32_e32 v23, 0xbfb8aa3b, v23
	v_exp_f32_e32 v109, v23
	s_nop 0
	v_sub_f32_e32 v23, 1.0, v109
	v_add_f32_e32 v25, 1.0, v109
	v_mul_f32_e32 v23, v23, v25
	v_sqrt_f32_e32 v108, v23
	v_add_f32_e32 v23, v1, v53
	v_pk_mul_f32 v[110:111], v[22:23], v[108:109]
	s_nop 0
	v_add_f32_e32 v1, v110, v111
	v_mul_f32_e32 v22, v109, v24
	ds_bpermute_b32 v23, v171, v22
	ds_bpermute_b32 v24, v171, v1
	s_waitcnt lgkmcnt(1)
	v_mul_f32_e32 v27, v22, v23
	s_waitcnt lgkmcnt(0)
	v_cndmask_b32_e64 v26, v24, 0, s[54:55]
	v_fma_f32 v22, v22, v24, v1
	v_fmac_f32_e32 v24, v1, v23
	v_cndmask_b32_e64 v25, v23, 1.0, s[54:55]
	v_cndmask_b32_e64 v1, v22, v24, s[54:55]
	ds_bpermute_b32 v23, v172, v27
	ds_bpermute_b32 v24, v172, v1
	s_waitcnt lgkmcnt(1)
	v_mul_f32_e32 v22, v25, v23
	v_cndmask_b32_e64 v55, v22, v25, s[56:57]
	s_waitcnt lgkmcnt(0)
	v_fma_f32 v22, v25, v24, v26
	v_fma_f32 v25, v27, v24, v1
	v_fmac_f32_e32 v24, v1, v23
	v_cndmask_b32_e64 v57, v22, v26, s[56:57]
	v_mul_f32_e32 v22, v27, v23
	v_cndmask_b32_e64 v23, v25, v24, s[56:57]
	ds_write_b64 v175, v[22:23] offset:62720
	ds_read_b128 v[22:25], v132 offset:39680
	ds_read_b128 v[26:29], v132 offset:48896
	s_waitcnt lgkmcnt(1)
	v_mfma_f32_16x16x32_bf16 v[22:25], v[14:17], v[22:25], 0
	s_waitcnt lgkmcnt(0)
; #define LAS __attribute__((address_space(3)))
; #define MFMA16(a, b, c) __builtin_amdgcn_mfma_f32_16x16x32_bf16(a, b, c, 0, 0, 0)
; template <bool PHASE_B>
; __device__ __forceinline__ void lru_item(const Params& p, LAS unsigned char* lds, int ci, int ci_next, int jb, const int tid, v4u (&xvn)[3]) {
;     ...
;         for (int ct = 0; ct < 4; ++ct) {
;             f32x4 ga = (f32x4){0.f, 0.f, 0.f, 0.f}, gx = (f32x4){0.f, 0.f, 0.f, 0.f};
; #pragma unroll
;             for (int ks = 0; ks < 2; ++ks) {
;                 const bf16x8 wa = *(const LAS bf16x8*)(lds + LR_WG + ((dir * 2 + 0) * 64 + 16 * ct + fr) * 144 + (32 * ks + 8 * fq) * 2);
;                 const bf16x8 wx = *(const LAS bf16x8*)(lds + LR_WG + ((dir * 2 + 1) * 64 + 16 * ct + fr) * 144 + (32 * ks + 8 * fq) * 2);
;                 ga = MFMA16(af[ks], wa, ga); gx = MFMA16(af[ks], wx, gx); }
;             const int ch = 16 * ct + fr; const float bav = GC[(dir * 3 + 0) * 64 + ch], bxv = GC[(dir * 3 + 1) * 64 + ch], c8 = GC[(dir * 3 + 2) * 64 + ch];
;             float Al = 1.f, Hl = 0.f;
; #pragma unroll
;             for (int ee = 0; ee < 4; ++ee) { const int e = dir ? 3 - ee : ee;
;                 const float r = __builtin_amdgcn_rcpf(1.f + __expf(-(ga[e] + bav))), ig = __builtin_amdgcn_rcpf(1.f + __expf(-(gx[e] + bxv)));
;                 const float la = -c8 * r; const float a = __expf(la); const float u = __builtin_amdgcn_sqrtf((1.f - a) * (1.f + a)) * (ig * xc[ct][e]);
;                 av[dir][ct][e] = a; uv[dir][ct][e] = u; Hl = a * Hl + u; Al *= a; }
;             const int o = dir ? 3 - fq : fq; const bool odd = (o & 1) != 0, hi2 = (o & 2) != 0;
;             const float A1 = __shfl_xor(Al, 16), H1 = __shfl_xor(Hl, 16);
;             const float pxA = odd ? A1 : 1.f, pxH = odd ? H1 : 0.f;
;             const float gA = Al * A1, gH = odd ? (Al * H1 + Hl) : (A1 * Hl + H1);
;             const float A2 = __shfl_xor(gA, 32), H2 = __shfl_xor(gH, 32);
;             const float PA = hi2 ? pxA * A2 : pxA, PH = hi2 ? (pxA * H2 + pxH) : pxH;
;             const float TA = gA * A2, TH = hi2 ? (gA * H2 + gH) : (A2 * gH + H2);
;             pA[dir][ct] = PA; pH[dir][ct] = PH;
;             ((LAS f32x2*)(lds + LR_SEG))[(dir * 8 + rt) * 64 + ch] = (f32x2){TA, TH};
	v_mfma_f32_16x16x32_bf16 v[114:117], v[14:17], v[26:29], 0
	ds_read_b128 v[26:29], v132 offset:39744
	ds_read_b128 v[138:141], v132 offset:48960
	ds_read_b32 v62, v174 offset:57920
	ds_read_b32 v64, v174 offset:58176
	ds_read_b32 v67, v174 offset:58432
	s_waitcnt lgkmcnt(4)
	v_mfma_f32_16x16x32_bf16 v[26:29], v[18:21], v[26:29], v[22:25]
	s_waitcnt lgkmcnt(3)
	v_mfma_f32_16x16x32_bf16 v[22:25], v[18:21], v[138:141], v[114:117]
	s_waitcnt lgkmcnt(2)
	s_nop 4
	v_add_f32_e32 v1, v29, v62
	v_mul_f32_e32 v1, 0xbfb8aa3b, v1
	v_exp_f32_e32 v1, v1
	s_nop 0
	v_add_f32_e32 v1, 1.0, v1
	v_rcp_f32_e32 v1, v1
	s_waitcnt lgkmcnt(1)
	v_add_f32_e32 v25, v25, v64
	v_mul_f32_e32 v25, 0xbfb8aa3b, v25
	v_exp_f32_e32 v25, v25
	s_waitcnt lgkmcnt(0)
	v_mul_f32_e32 v1, v1, v67
	v_mul_f32_e32 v1, 0xbfb8aa3b, v1
	v_exp_f32_e32 v112, v1
	v_add_f32_e32 v25, 1.0, v25
	v_rcp_f32_e32 v25, v25
	v_add_f32_e32 v23, v23, v64
	v_sub_f32_e32 v1, 1.0, v112
	v_add_f32_e32 v29, 1.0, v112
	v_mul_f32_e32 v1, v1, v29
	v_sqrt_f32_e32 v1, v1
	v_mul_f32_e32 v113, v113, v25
	v_mul_f32_e32 v23, 0xbfb8aa3b, v23
	v_exp_f32_e32 v23, v23
	v_pk_mul_f32 v[114:115], v[112:113], v[0:1]
	v_add_f32_e32 v24, v24, v64
	v_pk_fma_f32 v[126:127], v[112:113], v[0:1], v[114:115] op_sel_hi:[1,1,0]
	v_add_f32_e32 v1, v28, v62
	v_mul_f32_e32 v1, 0xbfb8aa3b, v1
	v_exp_f32_e32 v1, v1
	v_add_f32_e32 v23, 1.0, v23
	v_rcp_f32_e32 v23, v23
	v_mul_f32_e32 v24, 0xbfb8aa3b, v24
	v_add_f32_e32 v1, 1.0, v1
	v_rcp_f32_e32 v1, v1
	v_mul_f32_e32 v23, v120, v23
	v_exp_f32_e32 v24, v24
	v_add_f32_e32 v22, v22, v64
	v_mul_f32_e32 v1, v1, v67
	v_mul_f32_e32 v1, 0xbfb8aa3b, v1
	v_exp_f32_e32 v117, v1
	v_mul_f32_e32 v22, 0xbfb8aa3b, v22
	v_add_f32_e32 v24, 1.0, v24
	v_exp_f32_e32 v22, v22
	v_sub_f32_e32 v1, 1.0, v117
	v_add_f32_e32 v25, 1.0, v117
	v_mul_f32_e32 v1, v1, v25
	v_add_f32_e32 v25, v27, v62
	v_mul_f32_e32 v25, 0xbfb8aa3b, v25
	v_exp_f32_e32 v25, v25
	v_rcp_f32_e32 v24, v24
	v_sqrt_f32_e32 v116, v1
	v_add_f32_e32 v22, 1.0, v22
	v_add_f32_e32 v25, 1.0, v25
	v_rcp_f32_e32 v25, v25
	v_mul_f32_e32 v126, v118, v24
	v_rcp_f32_e32 v22, v22
	v_pk_mul_f32 v[118:119], v[126:127], v[116:117]
	v_mul_f32_e32 v25, v25, v67
	v_mul_f32_e32 v25, 0xbfb8aa3b, v25
	v_exp_f32_e32 v58, v25
	v_add_f32_e32 v1, v118, v119
	v_mul_f32_e32 v24, v112, v117
	v_mul_f32_e32 v22, v122, v22
	v_sub_f32_e32 v25, 1.0, v58
	v_add_f32_e32 v27, 1.0, v58
	v_mul_f32_e32 v25, v25, v27
	v_sqrt_f32_e32 v25, v25
	v_mul_f32_e32 v1, v58, v1
	v_mul_f32_e32 v24, v58, v24
	v_mul_f32_e32 v60, v23, v25
	v_add_f32_e32 v23, v26, v62
	v_mul_f32_e32 v23, 0xbfb8aa3b, v23
	v_exp_f32_e32 v23, v23
	s_nop 0
	v_add_f32_e32 v23, 1.0, v23
	v_rcp_f32_e32 v23, v23
	s_nop 0
	v_mul_f32_e32 v23, v23, v67
	v_mul_f32_e32 v23, 0xbfb8aa3b, v23
	v_exp_f32_e32 v121, v23
	s_nop 0
	v_sub_f32_e32 v23, 1.0, v121
	v_add_f32_e32 v25, 1.0, v121
	v_mul_f32_e32 v23, v23, v25
	v_sqrt_f32_e32 v120, v23
	v_add_f32_e32 v23, v1, v60
	v_pk_mul_f32 v[122:123], v[22:23], v[120:121]
	s_nop 0
	v_add_f32_e32 v1, v122, v123
	v_mul_f32_e32 v22, v121, v24
	ds_bpermute_b32 v23, v171, v22
	ds_bpermute_b32 v24, v171, v1
	s_waitcnt lgkmcnt(1)
	v_mul_f32_e32 v27, v22, v23
	s_waitcnt lgkmcnt(0)
	v_cndmask_b32_e64 v26, v24, 0, s[54:55]
	v_fma_f32 v22, v22, v24, v1
	v_fmac_f32_e32 v24, v1, v23
	v_cndmask_b32_e64 v25, v23, 1.0, s[54:55]
	v_cndmask_b32_e64 v1, v22, v24, s[54:55]
	ds_bpermute_b32 v23, v172, v27
	ds_bpermute_b32 v24, v172, v1
	s_waitcnt lgkmcnt(1)
	v_mul_f32_e32 v22, v25, v23
	v_cndmask_b32_e64 v62, v22, v25, s[56:57]
	s_waitcnt lgkmcnt(0)
	v_fma_f32 v22, v25, v24, v26
	v_fma_f32 v25, v27, v24, v1
	v_fmac_f32_e32 v24, v1, v23
	v_cndmask_b32_e64 v64, v22, v26, s[56:57]
	v_mul_f32_e32 v22, v27, v23
	v_cndmask_b32_e64 v23, v25, v24, s[56:57]
	ds_write_b64 v175, v[22:23] offset:62848
	ds_read_b128 v[22:25], v132 offset:41984
	ds_read_b128 v[26:29], v132 offset:51200
	s_waitcnt lgkmcnt(1)
	v_mfma_f32_16x16x32_bf16 v[22:25], v[14:17], v[22:25], 0
	s_waitcnt lgkmcnt(0)
	v_mfma_f32_16x16x32_bf16 v[138:141], v[14:17], v[26:29], 0
	ds_read_b128 v[26:29], v132 offset:42048
	ds_read_b128 v[150:153], v132 offset:51264
	ds_read_b32 v73, v174 offset:57984
	ds_read_b32 v74, v174 offset:58240
	ds_read_b32 v76, v174 offset:58496
	s_waitcnt lgkmcnt(4)
	v_mfma_f32_16x16x32_bf16 v[26:29], v[18:21], v[26:29], v[22:25]
	s_waitcnt lgkmcnt(3)
	v_mfma_f32_16x16x32_bf16 v[22:25], v[18:21], v[150:153], v[138:141]
	s_waitcnt lgkmcnt(2)
	s_nop 4
	v_add_f32_e32 v1, v29, v73
	v_mul_f32_e32 v1, 0xbfb8aa3b, v1
	v_exp_f32_e32 v1, v1
	s_nop 0
	v_add_f32_e32 v1, 1.0, v1
	v_rcp_f32_e32 v1, v1
	s_waitcnt lgkmcnt(1)
	v_add_f32_e32 v25, v25, v74
	v_mul_f32_e32 v25, 0xbfb8aa3b, v25
	v_exp_f32_e32 v25, v25
	s_waitcnt lgkmcnt(0)
; #define LAS __attribute__((address_space(3)))
; #define MFMA16(a, b, c) __builtin_amdgcn_mfma_f32_16x16x32_bf16(a, b, c, 0, 0, 0)
; template <bool PHASE_B>
; __device__ __forceinline__ void lru_item(const Params& p, LAS unsigned char* lds, int ci, int ci_next, int jb, const int tid, v4u (&xvn)[3]) {
;     ...
;         for (int ct = 0; ct < 4; ++ct) {
;             f32x4 ga = (f32x4){0.f, 0.f, 0.f, 0.f}, gx = (f32x4){0.f, 0.f, 0.f, 0.f};
; #pragma unroll
;             for (int ks = 0; ks < 2; ++ks) {
;                 const bf16x8 wa = *(const LAS bf16x8*)(lds + LR_WG + ((dir * 2 + 0) * 64 + 16 * ct + fr) * 144 + (32 * ks + 8 * fq) * 2);
;                 const bf16x8 wx = *(const LAS bf16x8*)(lds + LR_WG + ((dir * 2 + 1) * 64 + 16 * ct + fr) * 144 + (32 * ks + 8 * fq) * 2);
;                 ga = MFMA16(af[ks], wa, ga); gx = MFMA16(af[ks], wx, gx); }
;             const int ch = 16 * ct + fr; const float bav = GC[(dir * 3 + 0) * 64 + ch], bxv = GC[(dir * 3 + 1) * 64 + ch], c8 = GC[(dir * 3 + 2) * 64 + ch];
;             float Al = 1.f, Hl = 0.f;
; #pragma unroll
;             for (int ee = 0; ee < 4; ++ee) { const int e = dir ? 3 - ee : ee;
;                 const float r = __builtin_amdgcn_rcpf(1.f + __expf(-(ga[e] + bav))), ig = __builtin_amdgcn_rcpf(1.f + __expf(-(gx[e] + bxv)));
;                 const float la = -c8 * r; const float a = __expf(la); const float u = __builtin_amdgcn_sqrtf((1.f - a) * (1.f + a)) * (ig * xc[ct][e]);
;                 av[dir][ct][e] = a; uv[dir][ct][e] = u; Hl = a * Hl + u; Al *= a; }
;             const int o = dir ? 3 - fq : fq; const bool odd = (o & 1) != 0, hi2 = (o & 2) != 0;
;             const float A1 = __shfl_xor(Al, 16), H1 = __shfl_xor(Hl, 16);
;             const float pxA = odd ? A1 : 1.f, pxH = odd ? H1 : 0.f;
;             const float gA = Al * A1, gH = odd ? (Al * H1 + Hl) : (A1 * Hl + H1);
;             const float A2 = __shfl_xor(gA, 32), H2 = __shfl_xor(gH, 32);
;             const float PA = hi2 ? pxA * A2 : pxA, PH = hi2 ? (pxA * H2 + pxH) : pxH;
;             const float TA = gA * A2, TH = hi2 ? (gA * H2 + gH) : (A2 * gH + H2);
;             pA[dir][ct] = PA; pH[dir][ct] = PH;
;             ((LAS f32x2*)(lds + LR_SEG))[(dir * 8 + rt) * 64 + ch] = (f32x2){TA, TH};
	v_mul_f32_e32 v1, v1, v76
	v_mul_f32_e32 v1, 0xbfb8aa3b, v1
	v_exp_f32_e32 v124, v1
	v_add_f32_e32 v25, 1.0, v25
	v_rcp_f32_e32 v25, v25
	v_add_f32_e32 v24, v24, v74
	v_sub_f32_e32 v1, 1.0, v124
	v_add_f32_e32 v29, 1.0, v124
	v_mul_f32_e32 v1, v1, v29
	v_sqrt_f32_e32 v1, v1
	v_mul_f32_e32 v125, v125, v25
	v_mul_f32_e32 v24, 0xbfb8aa3b, v24
	v_exp_f32_e32 v24, v24
	v_pk_mul_f32 v[126:127], v[124:125], v[0:1]
	v_add_f32_e32 v23, v23, v74
	v_pk_fma_f32 v[134:135], v[124:125], v[0:1], v[126:127] op_sel_hi:[1,1,0]
	v_add_f32_e32 v1, v28, v73
	v_mul_f32_e32 v1, 0xbfb8aa3b, v1
	v_exp_f32_e32 v1, v1
	v_add_f32_e32 v24, 1.0, v24
	v_rcp_f32_e32 v24, v24
	v_mul_f32_e32 v23, 0xbfb8aa3b, v23
	v_add_f32_e32 v1, 1.0, v1
	v_rcp_f32_e32 v1, v1
	v_mul_f32_e32 v134, v128, v24
	v_exp_f32_e32 v23, v23
	v_add_f32_e32 v22, v22, v74
	v_mul_f32_e32 v1, v1, v76
	v_mul_f32_e32 v1, 0xbfb8aa3b, v1
	v_exp_f32_e32 v29, v1
	v_add_f32_e32 v23, 1.0, v23
	v_rcp_f32_e32 v23, v23
	v_mul_f32_e32 v22, 0xbfb8aa3b, v22
	v_sub_f32_e32 v1, 1.0, v29
	v_add_f32_e32 v25, 1.0, v29
	v_mul_f32_e32 v1, v1, v25
	v_add_f32_e32 v25, v27, v73
	v_mul_f32_e32 v25, 0xbfb8aa3b, v25
	v_exp_f32_e32 v25, v25
	v_sqrt_f32_e32 v28, v1
	v_mul_f32_e32 v23, v130, v23
	v_exp_f32_e32 v22, v22
	v_add_f32_e32 v25, 1.0, v25
	v_rcp_f32_e32 v25, v25
	v_pk_mul_f32 v[128:129], v[134:135], v[28:29]
	v_add_f32_e32 v22, 1.0, v22
	v_rcp_f32_e32 v22, v22
	v_mul_f32_e32 v25, v25, v76
	v_mul_f32_e32 v25, 0xbfb8aa3b, v25
	v_exp_f32_e32 v28, v25
	v_add_f32_e32 v1, v128, v129
	v_mul_f32_e32 v24, v124, v29
	v_mul_f32_e32 v22, v69, v22
	v_sub_f32_e32 v25, 1.0, v28
	v_add_f32_e32 v27, 1.0, v28
	v_mul_f32_e32 v25, v25, v27
	v_sqrt_f32_e32 v25, v25
	v_mul_f32_e32 v1, v28, v1
	v_mul_f32_e32 v24, v28, v24
	v_mul_f32_e32 v67, v23, v25
	v_add_f32_e32 v23, v26, v73
	v_mul_f32_e32 v23, 0xbfb8aa3b, v23
	v_exp_f32_e32 v23, v23
	s_nop 0
	v_add_f32_e32 v23, 1.0, v23
	v_rcp_f32_e32 v23, v23
	s_nop 0
	v_mul_f32_e32 v23, v23, v76
	v_mul_f32_e32 v23, 0xbfb8aa3b, v23
	v_exp_f32_e32 v27, v23
	s_nop 0
	v_sub_f32_e32 v23, 1.0, v27
	v_add_f32_e32 v25, 1.0, v27
	v_mul_f32_e32 v23, v23, v25
	v_sqrt_f32_e32 v26, v23
	v_add_f32_e32 v23, v1, v67
	v_pk_mul_f32 v[130:131], v[22:23], v[26:27]
	s_nop 0
	v_add_f32_e32 v1, v130, v131
	v_mul_f32_e32 v22, v27, v24
	ds_bpermute_b32 v23, v171, v22
	ds_bpermute_b32 v24, v171, v1
	s_waitcnt lgkmcnt(1)
	v_mul_f32_e32 v73, v22, v23
	s_waitcnt lgkmcnt(0)
	v_cndmask_b32_e64 v69, v24, 0, s[54:55]
	v_fma_f32 v22, v22, v24, v1
	v_fmac_f32_e32 v24, v1, v23
	v_cndmask_b32_e64 v25, v23, 1.0, s[54:55]
	v_cndmask_b32_e64 v1, v22, v24, s[54:55]
	ds_bpermute_b32 v23, v172, v73
	ds_bpermute_b32 v24, v172, v1
	s_waitcnt lgkmcnt(1)
	v_mul_f32_e32 v22, v25, v23
	v_cndmask_b32_e64 v26, v22, v25, s[56:57]
	s_waitcnt lgkmcnt(0)
	v_fma_f32 v22, v25, v24, v69
	v_fma_f32 v25, v73, v24, v1
	v_fmac_f32_e32 v24, v1, v23
	v_cndmask_b32_e64 v69, v22, v69, s[56:57]
	v_mul_f32_e32 v22, v73, v23
	v_cndmask_b32_e64 v23, v25, v24, s[56:57]
	ds_write_b64 v175, v[22:23] offset:62976
	ds_read_b128 v[22:25], v132 offset:44288
	ds_read_b128 v[138:141], v132 offset:53504
	s_waitcnt lgkmcnt(1)
	v_mfma_f32_16x16x32_bf16 v[22:25], v[14:17], v[22:25], 0
	s_waitcnt lgkmcnt(0)
	v_mfma_f32_16x16x32_bf16 v[14:17], v[14:17], v[138:141], 0
	ds_read_b128 v[138:141], v132 offset:44352
	ds_read_b128 v[150:153], v132 offset:53568
	s_waitcnt lgkmcnt(1)
	v_mfma_f32_16x16x32_bf16 v[22:25], v[18:21], v[138:141], v[22:25]
	s_waitcnt lgkmcnt(0)
	v_mfma_f32_16x16x32_bf16 v[14:17], v[18:21], v[150:153], v[14:17]
	ds_read_b32 v20, v174 offset:58048
	ds_read_b32 v21, v174 offset:58304
	ds_read_b32 v73, v174 offset:58560
	s_waitcnt lgkmcnt(2)
	s_nop 1
	v_add_f32_e32 v1, v25, v20
	v_mul_f32_e32 v1, 0xbfb8aa3b, v1
	v_exp_f32_e32 v1, v1
	s_waitcnt lgkmcnt(1)
	v_add_f32_e32 v17, v17, v21
	v_mul_f32_e32 v17, 0xbfb8aa3b, v17
	v_exp_f32_e32 v17, v17
	v_add_f32_e32 v1, 1.0, v1
	v_rcp_f32_e32 v1, v1
	v_add_f32_e32 v16, v16, v21
	v_add_f32_e32 v17, 1.0, v17
	v_rcp_f32_e32 v17, v17
	s_waitcnt lgkmcnt(0)
	v_mul_f32_e32 v1, v1, v73
	v_mul_f32_e32 v1, 0xbfb8aa3b, v1
	v_exp_f32_e32 v132, v1
	v_mul_f32_e32 v133, v133, v17
	v_mul_f32_e32 v16, 0xbfb8aa3b, v16
	v_exp_f32_e32 v16, v16
	v_sub_f32_e32 v1, 1.0, v132
	v_add_f32_e32 v18, 1.0, v132
	v_mul_f32_e32 v1, v1, v18
	v_sqrt_f32_e32 v1, v1
	v_add_f32_e32 v16, 1.0, v16
	v_add_f32_e32 v15, v15, v21
	v_rcp_f32_e32 v16, v16
	v_pk_mul_f32 v[134:135], v[132:133], v[0:1]
	v_mul_f32_e32 v15, 0xbfb8aa3b, v15
	v_pk_fma_f32 v[18:19], v[132:133], v[0:1], v[134:135] op_sel_hi:[1,1,0]
	v_add_f32_e32 v1, v24, v20
	v_mul_f32_e32 v1, 0xbfb8aa3b, v1
	v_exp_f32_e32 v1, v1
	v_exp_f32_e32 v15, v15
	v_mul_f32_e32 v18, v136, v16
	v_add_f32_e32 v14, v14, v21
	v_add_f32_e32 v1, 1.0, v1
	v_rcp_f32_e32 v1, v1
	v_add_f32_e32 v15, 1.0, v15
	v_rcp_f32_e32 v15, v15
	v_mul_f32_e32 v14, 0xbfb8aa3b, v14
	v_mul_f32_e32 v1, v1, v73
	v_mul_f32_e32 v1, 0xbfb8aa3b, v1
	v_exp_f32_e32 v25, v1
	v_mul_f32_e32 v15, v31, v15
	v_exp_f32_e32 v14, v14
	v_sub_f32_e32 v1, 1.0, v25
	v_add_f32_e32 v17, 1.0, v25
	v_mul_f32_e32 v1, v1, v17
	v_sqrt_f32_e32 v24, v1
	v_add_f32_e32 v1, v23, v20
	v_mul_f32_e32 v1, 0xbfb8aa3b, v1
	v_exp_f32_e32 v1, v1
	v_pk_mul_f32 v[136:137], v[18:19], v[24:25]
	v_mul_f32_e32 v17, v132, v25
	v_add_f32_e32 v16, v136, v137
	v_add_f32_e32 v1, 1.0, v1
	v_rcp_f32_e32 v1, v1
	v_add_f32_e32 v14, 1.0, v14
	v_rcp_f32_e32 v14, v14
	v_mul_f32_e32 v1, v1, v73
	v_mul_f32_e32 v1, 0xbfb8aa3b, v1
	v_exp_f32_e32 v1, v1
	v_mul_f32_e32 v14, v71, v14
	v_sub_f32_e32 v18, 1.0, v1
	v_add_f32_e32 v19, 1.0, v1
	v_mul_f32_e32 v18, v18, v19
	v_sqrt_f32_e32 v18, v18
	s_nop 0
	v_mul_f32_e32 v24, v15, v18
	v_mul_f32_e32 v15, v1, v16
	v_mul_f32_e32 v16, v1, v17
	v_add_f32_e32 v17, v22, v20
	v_mul_f32_e32 v17, 0xbfb8aa3b, v17
	v_exp_f32_e32 v17, v17
	v_add_f32_e32 v15, v15, v24
	v_add_f32_e32 v17, 1.0, v17
	v_rcp_f32_e32 v17, v17
	s_nop 0
	v_mul_f32_e32 v17, v17, v73
	v_mul_f32_e32 v17, 0xbfb8aa3b, v17
	v_exp_f32_e32 v23, v17
	s_nop 0
	v_sub_f32_e32 v17, 1.0, v23
	v_add_f32_e32 v18, 1.0, v23
	v_mul_f32_e32 v17, v17, v18
	v_sqrt_f32_e32 v22, v17
	s_nop 0
	v_pk_mul_f32 v[138:139], v[14:15], v[22:23]
	s_nop 0
	v_add_f32_e32 v14, v138, v139
	v_mul_f32_e32 v15, v23, v16
	ds_bpermute_b32 v16, v171, v15
	ds_bpermute_b32 v17, v171, v14
	s_waitcnt lgkmcnt(1)
; #define LAS __attribute__((address_space(3)))
; template <bool PHASE_B>
; __device__ __forceinline__ void lru_item(const Params& p, LAS unsigned char* lds, int ci, int ci_next, int jb, const int tid, v4u (&xvn)[3]) {
;     ...
;             const int o = dir ? 3 - fq : fq; const bool odd = (o & 1) != 0, hi2 = (o & 2) != 0;
;             const float A1 = __shfl_xor(Al, 16), H1 = __shfl_xor(Hl, 16);
;             const float pxA = odd ? A1 : 1.f, pxH = odd ? H1 : 0.f;
;             const float gA = Al * A1, gH = odd ? (Al * H1 + Hl) : (A1 * Hl + H1);
;             const float A2 = __shfl_xor(gA, 32), H2 = __shfl_xor(gH, 32);
;             const float PA = hi2 ? pxA * A2 : pxA, PH = hi2 ? (pxA * H2 + pxH) : pxH;
;             const float TA = gA * A2, TH = hi2 ? (gA * H2 + gH) : (A2 * gH + H2);
;             pA[dir][ct] = PA; pH[dir][ct] = PH;
;             ((LAS f32x2*)(lds + LR_SEG))[(dir * 8 + rt) * 64 + ch] = (f32x2){TA, TH};
;         }
;     }
;     if constexpr (PHASE_B) {
; #pragma unroll
;         for (int dir = 0; dir < 2; ++dir)
; #pragma unroll
;             for (int ct = 0; ct < 4; ++ct) cin[dir][ct] = ((const float*)(p.ws + WS_CIN))[(size_t)(ci * 2 + dir) * 768 + jb * 64 + 16 * ct + fr];
;         const bf16* gp = (const bf16*)(p.ws + WS_GR) + (size_t)(t0 + (tid >> 2)) * 768 + jb * 64 + (tid & 3) * 16;
;         gv[0] = *(const v4u*)gp; gv[1] = *(const v4u*)(gp + 8);
;     }
;     __syncthreads();
;     if constexpr (!PHASE_B) {
;         if (tid < 128) { const int dir = tid >> 6, ch = tid & 63; float A = 1.f, H = 0.f;
; #pragma unroll
;             for (int q = 0; q < 8; ++q) { const f32x2 sh = ((const LAS f32x2*)(lds + LR_SEG))[(dir * 8 + (dir ? 7 - q : q)) * 64 + ch]; H = sh.x * H + sh.y; A *= sh.x; }
;             ((f32x2*)(p.ws + WS_CAR))[(size_t)(ci * 2 + dir) * 768 + jb * 64 + ch] = (f32x2){A, H}; }
;     } else {
; #pragma unroll
;         for (int dir = 0; dir < 2; ++dir) { const int ot = dir ? 7 - rt : rt;
; #pragma unroll
;             for (int ct = 0; ct < 4; ++ct) { const int ch = 16 * ct + fr; float h = cin[dir][ct];
; #pragma unroll
;                 for (int q = 0; q < 7; ++q) { const f32x2 sh = ((const LAS f32x2*)(lds + LR_SEG))[(dir * 8 + (dir ? 7 - q : q)) * 64 + ch]; const float nh = sh.x * h + sh.y; h = (q < ot) ? nh : h; }
;                 h = pA[dir][ct] * h + pH[dir][ct];
; #pragma unroll
	v_mul_f32_e32 v20, v15, v16
	s_waitcnt lgkmcnt(0)
	v_cndmask_b32_e64 v19, v17, 0, s[54:55]
	v_fma_f32 v15, v15, v17, v14
	v_fmac_f32_e32 v17, v14, v16
	v_cndmask_b32_e64 v18, v16, 1.0, s[54:55]
	v_cndmask_b32_e64 v15, v15, v17, s[54:55]
	ds_bpermute_b32 v16, v172, v20
	ds_bpermute_b32 v17, v172, v15
	s_waitcnt lgkmcnt(1)
	v_mul_f32_e32 v14, v18, v16
	v_cndmask_b32_e64 v22, v14, v18, s[56:57]
	s_waitcnt lgkmcnt(0)
	v_fma_f32 v14, v18, v17, v19
	v_fma_f32 v18, v20, v17, v15
	v_fmac_f32_e32 v17, v15, v16
	v_cndmask_b32_e64 v31, v14, v19, s[56:57]
	v_mul_f32_e32 v14, v20, v16
	v_cndmask_b32_e64 v15, v18, v17, s[56:57]
	ds_write_b64 v175, v[14:15] offset:63104
	v_mad_i64_i32 v[14:15], s[0:1], s13, v232, v[32:33]
	global_load_dword v78, v[14:15], off
	global_load_dword v81, v[14:15], off offset:64
	global_load_dword v83, v[14:15], off offset:128
	global_load_dword v85, v[14:15], off offset:192
	s_add_i32 s0, s13, 1
	v_mad_i64_i32 v[14:15], s[0:1], s0, v232, v[32:33]
	s_movk_i32 s0, 0x600
	s_nop 0
	v_mad_i64_i32 v[140:141], s[0:1], v196, s0, v[34:35]
	global_load_dword v76, v[14:15], off
	global_load_dword v74, v[14:15], off offset:64
	global_load_dword v73, v[14:15], off offset:128
	global_load_dword v71, v[14:15], off offset:192
	s_nop 0
	global_load_dwordx4 v[14:17], v[140:141], off offset:16
	global_load_dwordx4 v[18:21], v[140:141], off
	s_waitcnt lgkmcnt(0)
	s_barrier
	ds_read_b64 v[208:209], v176 offset:58624
	ds_read_b64 v[210:211], v176 offset:59136
	ds_read_b64 v[212:213], v176 offset:59648
	ds_read_b64 v[214:215], v176 offset:60160
	ds_read_b64 v[216:217], v176 offset:60672
	ds_read_b64 v[218:219], v176 offset:61184
	ds_read_b64 v[220:221], v176 offset:61696
	v_add_u32_e32 v196, s12, v196
	s_add_i32 s13, s13, s86
	s_waitcnt vmcnt(9) lgkmcnt(0)
	v_fmac_f32_e32 v209, v78, v208
	v_cndmask_b32_e64 v78, v78, v209, s[58:59]
	v_fmac_f32_e32 v211, v210, v78
	v_cndmask_b32_e64 v78, v78, v211, s[60:61]
	v_fmac_f32_e32 v213, v212, v78
	v_cndmask_b32_e64 v78, v78, v213, s[62:63]
	v_fmac_f32_e32 v215, v214, v78
	v_cndmask_b32_e64 v78, v78, v215, s[64:65]
	v_fmac_f32_e32 v217, v216, v78
	v_cndmask_b32_e64 v78, v78, v217, s[66:67]
	v_fmac_f32_e32 v219, v218, v78
	v_cndmask_b32_e64 v78, v78, v219, s[68:69]
	v_fmac_f32_e32 v221, v220, v78
	v_cndmask_b32_e64 v78, v78, v221, s[70:71]
	v_fmac_f32_e32 v39, v206, v78
	v_fmac_f32_e32 v49, v38, v39
	v_fmac_f32_e32 v50, v41, v49
	v_fmac_f32_e32 v52, v43, v50
	v_fmac_f32_e32 v54, v47, v52
	ds_write2_b32 v202, v49, v50 offset1:68
	ds_write2_b32 v202, v52, v54 offset0:136 offset1:204
	ds_read_b64 v[222:223], v176 offset:58752
	ds_read_b64 v[224:225], v176 offset:59264
	ds_read_b64 v[226:227], v176 offset:59776
	ds_read_b64 v[228:229], v176 offset:60288
	ds_read_b64 v[234:235], v176 offset:60800
	ds_read_b64 v[236:237], v176 offset:61312
	ds_read_b64 v[238:239], v176 offset:61824
	s_waitcnt vmcnt(0)
	v_lshlrev_b32_e32 v52, 16, v18
	v_and_b32_e32 v18, 0xffff0000, v18
	s_waitcnt lgkmcnt(0)
	v_fmac_f32_e32 v223, v81, v222
	v_cndmask_b32_e64 v41, v81, v223, s[58:59]
	v_fmac_f32_e32 v225, v224, v41
	v_cndmask_b32_e64 v41, v41, v225, s[60:61]
	v_fmac_f32_e32 v227, v226, v41
	v_cndmask_b32_e64 v41, v41, v227, s[62:63]
	v_fmac_f32_e32 v229, v228, v41
	v_cndmask_b32_e64 v41, v41, v229, s[64:65]
	v_fmac_f32_e32 v235, v234, v41
	v_cndmask_b32_e64 v41, v41, v235, s[66:67]
	v_fmac_f32_e32 v237, v236, v41
	v_cndmask_b32_e64 v41, v41, v237, s[68:69]
	v_fmac_f32_e32 v239, v238, v41
	v_cndmask_b32_e64 v38, v41, v239, s[70:71]
	v_fmac_f32_e32 v42, v40, v38
	v_fmac_f32_e32 v65, v56, v42
	v_fmac_f32_e32 v66, v59, v65
	v_fmac_f32_e32 v68, v61, v66
	v_fmac_f32_e32 v70, v63, v68
	ds_write_b32 v177, v65
	ds_write_b32 v178, v66
	ds_write_b32 v179, v68
	ds_write_b32 v180, v70
	ds_read_b64 v[208:209], v176 offset:58880
	ds_read_b64 v[210:211], v176 offset:59392
	ds_read_b64 v[212:213], v176 offset:59904
	ds_read_b64 v[214:215], v176 offset:60416
	ds_read_b64 v[216:217], v176 offset:60928
	ds_read_b64 v[218:219], v176 offset:61440
	ds_read_b64 v[220:221], v176 offset:61952
	s_waitcnt lgkmcnt(0)
	v_fmac_f32_e32 v209, v83, v208
	v_cndmask_b32_e64 v40, v83, v209, s[58:59]
	v_fmac_f32_e32 v211, v210, v40
	v_cndmask_b32_e64 v40, v40, v211, s[60:61]
	v_fmac_f32_e32 v213, v212, v40
	v_cndmask_b32_e64 v40, v40, v213, s[62:63]
	v_fmac_f32_e32 v215, v214, v40
	v_cndmask_b32_e64 v40, v40, v215, s[64:65]
	v_fmac_f32_e32 v217, v216, v40
	v_cndmask_b32_e64 v40, v40, v217, s[66:67]
	v_fmac_f32_e32 v219, v218, v40
	v_cndmask_b32_e64 v40, v40, v219, s[68:69]
	v_fmac_f32_e32 v221, v220, v40
	v_cndmask_b32_e64 v38, v40, v221, s[70:71]
	v_fmac_f32_e32 v44, v46, v38
	v_fmac_f32_e32 v45, v72, v44
	v_fmac_f32_e32 v80, v75, v45
	v_fmac_f32_e32 v82, v77, v80
	v_fmac_f32_e32 v84, v79, v82
	ds_write_b32 v181, v45
	ds_write_b32 v182, v80
	ds_write_b32 v183, v82
	ds_write_b32 v184, v84
	ds_read_b64 v[222:223], v176 offset:59008
	ds_read_b64 v[224:225], v176 offset:59520
	ds_read_b64 v[226:227], v176 offset:60032
	ds_read_b64 v[228:229], v176 offset:60544
	ds_read_b64 v[234:235], v176 offset:61056
	ds_read_b64 v[236:237], v176 offset:61568
	ds_read_b64 v[238:239], v176 offset:62080
	s_waitcnt lgkmcnt(0)
	v_fmac_f32_e32 v223, v85, v222
	v_cndmask_b32_e64 v40, v85, v223, s[58:59]
	v_fmac_f32_e32 v225, v224, v40
	v_cndmask_b32_e64 v40, v40, v225, s[60:61]
	v_fmac_f32_e32 v227, v226, v40
	v_cndmask_b32_e64 v40, v40, v227, s[62:63]
	v_fmac_f32_e32 v229, v228, v40
	v_cndmask_b32_e64 v40, v40, v229, s[64:65]
	v_fmac_f32_e32 v235, v234, v40
	v_cndmask_b32_e64 v40, v40, v235, s[66:67]
	v_fmac_f32_e32 v237, v236, v40
	v_cndmask_b32_e64 v40, v40, v237, s[68:69]
	v_fmac_f32_e32 v239, v238, v40
	v_cndmask_b32_e64 v38, v40, v239, s[70:71]
	v_fmac_f32_e32 v36, v48, v38
	v_fmac_f32_e32 v37, v86, v36
	v_fmac_f32_e32 v94, v89, v37
	v_fmac_f32_e32 v96, v91, v94
	v_fmac_f32_e32 v98, v93, v96
	ds_write_b32 v185, v37
	ds_write_b32 v186, v94
	ds_write_b32 v187, v96
	ds_write_b32 v188, v98
	ds_read2st64_b64 v[36:39], v190 offset0:6 offset1:7
	s_waitcnt lgkmcnt(0)
; #define LAS __attribute__((address_space(3)))
; template <bool PHASE_B>
; __device__ __forceinline__ void lru_item(const Params& p, LAS unsigned char* lds, int ci, int ci_next, int jb, const int tid, v4u (&xvn)[3]) {
;     ...
;         for (int dir = 0; dir < 2; ++dir) { const int ot = dir ? 7 - rt : rt;
; #pragma unroll
;             for (int ct = 0; ct < 4; ++ct) { const int ch = 16 * ct + fr; float h = cin[dir][ct];
; #pragma unroll
;                 for (int q = 0; q < 7; ++q) { const f32x2 sh = ((const LAS f32x2*)(lds + LR_SEG))[(dir * 8 + (dir ? 7 - q : q)) * 64 + ch]; const float nh = sh.x * h + sh.y; h = (q < ot) ? nh : h; }
;                 h = pA[dir][ct] * h + pH[dir][ct];
; #pragma unroll
;                 for (int ee = 0; ee < 4; ++ee) { const int e = dir ? 3 - ee : ee; h = av[dir][ct][e] * h + uv[dir][ct][e];
;                     ((LAS float*)(lds + LR_HB))[(dir * LCH + 16 * rt + 4 * fq + e) * 68 + ch] = h; } } }
	v_fma_f32 v38, v76, v38, v39
	v_cndmask_b32_e64 v38, v76, v38, s[72:73]
	v_fmac_f32_e32 v37, v36, v38
	v_cndmask_b32_e64 v38, v38, v37, s[74:75]
	ds_read_b64 v[208:209], v176 offset:65280
	ds_read_b64 v[210:211], v176 offset:64768
	ds_read_b64 v[212:213], v176 offset:64256
	ds_read_b64 v[214:215], v176 offset:63744
	ds_read_b64 v[216:217], v176 offset:63232
	s_waitcnt lgkmcnt(0)
	v_fmac_f32_e32 v209, v208, v38
	v_cndmask_b32_e64 v38, v38, v209, s[76:77]
	v_fmac_f32_e32 v211, v210, v38
	v_cndmask_b32_e64 v38, v38, v211, s[78:79]
	v_fmac_f32_e32 v213, v212, v38
	v_cndmask_b32_e64 v38, v38, v213, s[80:81]
	v_fmac_f32_e32 v215, v214, v38
	v_cndmask_b32_e64 v38, v38, v215, s[82:83]
	v_fmac_f32_e32 v217, v216, v38
	v_cndmask_b32_e64 v36, v38, v217, s[84:85]
	v_fmac_f32_e32 v57, v55, v36
	v_fmac_f32_e32 v103, v100, v57
	v_fmac_f32_e32 v106, v105, v103
	v_fmac_f32_e32 v53, v51, v106
	v_add_u32_e32 v36, 0x8800, v202
	v_fmac_f32_e32 v110, v109, v53
	ds_write2_b32 v36, v106, v103 offset0:136 offset1:204
	ds_write2_b32 v36, v110, v53 offset1:68
	ds_read2st64_b64 v[36:39], v191 offset0:6 offset1:7
	v_lshlrev_b32_e32 v53, 16, v19
	v_and_b32_e32 v19, 0xffff0000, v19
	s_waitcnt lgkmcnt(0)
	v_fma_f32 v38, v74, v38, v39
	v_cndmask_b32_e64 v38, v74, v38, s[72:73]
	v_fmac_f32_e32 v37, v36, v38
	v_cndmask_b32_e64 v38, v38, v37, s[74:75]
	ds_read_b64 v[222:223], v176 offset:65408
	ds_read_b64 v[224:225], v176 offset:64896
	ds_read_b64 v[226:227], v176 offset:64384
	ds_read_b64 v[228:229], v176 offset:63872
	ds_read_b64 v[234:235], v176 offset:63360
	s_waitcnt lgkmcnt(0)
	v_fmac_f32_e32 v223, v222, v38
	v_cndmask_b32_e64 v38, v38, v223, s[76:77]
	v_fmac_f32_e32 v225, v224, v38
	v_cndmask_b32_e64 v38, v38, v225, s[78:79]
	v_fmac_f32_e32 v227, v226, v38
	v_cndmask_b32_e64 v38, v38, v227, s[80:81]
	v_fmac_f32_e32 v229, v228, v38
	v_cndmask_b32_e64 v38, v38, v229, s[82:83]
	v_fmac_f32_e32 v235, v234, v38
	v_cndmask_b32_e64 v36, v38, v235, s[84:85]
	v_fmac_f32_e32 v64, v62, v36
	v_fmac_f32_e32 v115, v112, v64
	v_fmac_f32_e32 v118, v117, v115
	v_fmac_f32_e32 v60, v58, v118
	v_add_u32_e32 v36, 0x8800, v203
	v_fmac_f32_e32 v122, v121, v60
	ds_write2_b32 v36, v118, v115 offset0:136 offset1:204
	ds_write2_b32 v36, v122, v60 offset1:68
	ds_read_b64 v[36:37], v192 offset:3584
	s_waitcnt lgkmcnt(0)
	v_fmac_f32_e32 v37, v73, v36
	v_cndmask_b32_e64 v40, v73, v37, s[72:73]
	ds_read2st64_b64 v[36:39], v192 offset0:5 offset1:6
	s_waitcnt lgkmcnt(0)
	v_fma_f32 v38, v38, v40, v39
	v_cndmask_b32_e64 v38, v40, v38, s[74:75]
	v_fmac_f32_e32 v37, v36, v38
	v_cndmask_b32_e64 v38, v38, v37, s[76:77]
	ds_read_b64 v[208:209], v176 offset:65024
	ds_read_b64 v[210:211], v176 offset:64512
	ds_read_b64 v[212:213], v176 offset:64000
	ds_read_b64 v[214:215], v176 offset:63488
	s_waitcnt lgkmcnt(0)
	v_fmac_f32_e32 v209, v208, v38
	v_cndmask_b32_e64 v38, v38, v209, s[78:79]
	v_fmac_f32_e32 v211, v210, v38
	v_cndmask_b32_e64 v38, v38, v211, s[80:81]
	v_fmac_f32_e32 v213, v212, v38
	v_cndmask_b32_e64 v38, v38, v213, s[82:83]
	v_fmac_f32_e32 v215, v214, v38
	v_cndmask_b32_e64 v36, v38, v215, s[84:85]
	v_fmac_f32_e32 v69, v26, v36
	v_fmac_f32_e32 v127, v124, v69
	v_fmac_f32_e32 v128, v29, v127
	v_fmac_f32_e32 v67, v28, v128
	v_add_u32_e32 v26, 0x8800, v204
	v_fmac_f32_e32 v130, v27, v67
	ds_write2_b32 v26, v128, v127 offset0:136 offset1:204
	ds_write2_b32 v26, v130, v67 offset1:68
	ds_read_b64 v[26:27], v194 offset:3584
	s_waitcnt lgkmcnt(0)
	v_fmac_f32_e32 v27, v71, v26
	v_cndmask_b32_e64 v36, v71, v27, s[72:73]
	ds_read2st64_b64 v[26:29], v194 offset0:5 offset1:6
	s_waitcnt lgkmcnt(0)
	v_fma_f32 v28, v28, v36, v29
	v_cndmask_b32_e64 v28, v36, v28, s[74:75]
	v_fmac_f32_e32 v27, v26, v28
	v_cndmask_b32_e64 v28, v28, v27, s[76:77]
	ds_read_b64 v[222:223], v176 offset:65152
	ds_read_b64 v[224:225], v176 offset:64640
	ds_read_b64 v[226:227], v176 offset:64128
	ds_read_b64 v[228:229], v176 offset:63616
	s_waitcnt lgkmcnt(0)
	v_fmac_f32_e32 v223, v222, v28
	v_cndmask_b32_e64 v28, v28, v223, s[78:79]
	v_fmac_f32_e32 v225, v224, v28
	v_cndmask_b32_e64 v28, v28, v225, s[80:81]
	v_fmac_f32_e32 v227, v226, v28
	v_cndmask_b32_e64 v28, v28, v227, s[82:83]
	v_fmac_f32_e32 v229, v228, v28
	v_cndmask_b32_e64 v26, v28, v229, s[84:85]
	v_fmac_f32_e32 v31, v22, v26
	v_fmac_f32_e32 v135, v132, v31
	v_fmac_f32_e32 v136, v25, v135
	v_fmac_f32_e32 v24, v1, v136
	v_add_u32_e32 v22, 0x8800, v205
	v_fmac_f32_e32 v138, v23, v24
	ds_write2_b32 v22, v136, v135 offset0:136 offset1:204
	ds_write2_b32 v22, v138, v24 offset1:68
	s_waitcnt lgkmcnt(0)
	s_barrier
; #define LAS __attribute__((address_space(3)))
; __device__ __forceinline__ unsigned pk2(float lo, float hi) { return f2bf(lo) | (f2bf(hi) << 16); }
; template <bool PHASE_B>
; __device__ __forceinline__ void lru_item(const Params& p, LAS unsigned char* lds, int ci, int ci_next, int jb, const int tid, v4u (&xvn)[3]) {
;     ...
;         { const int t = tid >> 2, c0 = (tid & 3) * 16; bf16* gp = (bf16*)(p.ws + WS_GR) + (size_t)(t0 + t) * 768 + jb * 64 + c0;
;           const LAS float* H0 = (const LAS float*)(lds + LR_HB) + t * 68 + c0; const LAS float* H1 = H0 + LCH * 68;
; #pragma unroll
;           for (int hf = 0; hf < 2; ++hf) { const f32x4 a0 = *(const LAS f32x4*)(H0 + 8 * hf), a1 = *(const LAS f32x4*)(H0 + 8 * hf + 4), b0 = *(const LAS f32x4*)(H1 + 8 * hf), b1 = *(const LAS f32x4*)(H1 + 8 * hf + 4);
;               const v4u g = gv[hf]; v4u o;
;               o.x = pk2(bflo(g.x) * (a0[0] + b0[0]), bfhi(g.x) * (a0[1] + b0[1])); o.y = pk2(bflo(g.y) * (a0[2] + b0[2]), bfhi(g.y) * (a0[3] + b0[3]));
;               o.z = pk2(bflo(g.z) * (a1[0] + b1[0]), bfhi(g.z) * (a1[1] + b1[1])); o.w = pk2(bflo(g.w) * (a1[2] + b1[2]), bfhi(g.w) * (a1[3] + b1[3]));
;               *(v4u*)(gp + 8 * hf) = o; } }
	ds_read_b128 v[22:25], v195
	ds_read_b128 v[26:29], v195 offset:16
	ds_read_b128 v[36:39], v195 offset:32
	ds_read_b128 v[40:43], v195 offset:48
	ds_read_b128 v[44:47], v195 offset:34816
	ds_read_b128 v[48:51], v195 offset:34832
	s_waitcnt lgkmcnt(1)
	v_pk_add_f32 v[24:25], v[24:25], v[46:47]
	v_pk_add_f32 v[22:23], v[22:23], v[44:45]
	v_mov_b32_e32 v45, v24
	v_mov_b32_e32 v24, v23
	v_pk_mul_f32 v[18:19], v[24:25], v[18:19]
	s_waitcnt lgkmcnt(0)
	v_pk_add_f32 v[24:25], v[28:29], v[50:51]
	v_pk_add_f32 v[26:27], v[26:27], v[48:49]
	v_mov_b32_e32 v44, v22
	v_lshlrev_b32_e32 v23, 16, v21
	v_lshlrev_b32_e32 v22, 16, v20
	v_mov_b32_e32 v29, v24
	v_and_b32_e32 v21, 0xffff0000, v21
	v_and_b32_e32 v20, 0xffff0000, v20
	v_mov_b32_e32 v24, v27
	v_mov_b32_e32 v28, v26
	v_pk_mul_f32 v[20:21], v[24:25], v[20:21]
	v_pk_mul_f32 v[44:45], v[44:45], v[52:53]
	v_pk_mul_f32 v[22:23], v[28:29], v[22:23]
	v_bfe_u32 v1, v21, 16, 1
	v_add3_u32 v1, v21, v1, s33
	v_bfe_u32 v26, v23, 16, 1
	v_add3_u32 v23, v23, v26, s33
	v_lshrrev_b32_e32 v21, 16, v23
	v_and_or_b32 v21, v1, s11, v21
	v_cvt_pk_bf16_f32 v20, v22, v20
	v_cvt_pk_bf16_f32 v19, v45, v19
	v_cvt_pk_bf16_f32 v18, v44, v18
	global_store_dwordx4 v[140:141], v[18:21], off
	ds_read_b128 v[18:21], v195 offset:34848
	ds_read_b128 v[22:25], v195 offset:34864
	v_lshlrev_b32_e32 v27, 16, v15
	v_lshlrev_b32_e32 v26, 16, v14
	v_and_b32_e32 v15, 0xffff0000, v15
	s_waitcnt lgkmcnt(1)
	v_pk_add_f32 v[20:21], v[38:39], v[20:21]
	v_pk_add_f32 v[18:19], v[36:37], v[18:19]
	v_mov_b32_e32 v29, v20
	v_and_b32_e32 v14, 0xffff0000, v14
	v_mov_b32_e32 v20, v19
	v_pk_mul_f32 v[14:15], v[20:21], v[14:15]
	s_waitcnt lgkmcnt(0)
	v_pk_add_f32 v[20:21], v[42:43], v[24:25]
	v_pk_add_f32 v[22:23], v[40:41], v[22:23]
	v_mov_b32_e32 v28, v18
	v_lshlrev_b32_e32 v19, 16, v17
	v_lshlrev_b32_e32 v18, 16, v16
	v_mov_b32_e32 v25, v20
	v_and_b32_e32 v17, 0xffff0000, v17
	v_and_b32_e32 v16, 0xffff0000, v16
	v_mov_b32_e32 v20, v23
	v_mov_b32_e32 v24, v22
	v_pk_mul_f32 v[16:17], v[20:21], v[16:17]
	v_pk_mul_f32 v[26:27], v[28:29], v[26:27]
	v_pk_mul_f32 v[18:19], v[24:25], v[18:19]
	v_bfe_u32 v1, v17, 16, 1
	v_bfe_u32 v20, v16, 16, 1
	v_add3_u32 v16, v16, v20, s33
	v_add3_u32 v1, v17, v1, s33
	v_bfe_u32 v21, v18, 16, 1
	v_bfe_u32 v22, v19, 16, 1
	v_add3_u32 v19, v19, v22, s33
	v_add3_u32 v18, v18, v21, s33
	v_lshrrev_b32_e32 v21, 16, v17
	v_lshrrev_b32_e32 v20, 16, v20
	v_lshrrev_b32_e32 v18, 16, v18
	v_lshrrev_b32_e32 v17, 16, v19
	v_and_or_b32 v17, v1, s11, v17
	v_and_or_b32 v16, v16, s11, v18
	v_cvt_pk_bf16_f32 v15, v27, v15
	v_cvt_pk_bf16_f32 v14, v26, v14
	global_store_dwordx4 v[140:141], v[14:17], off offset:16
	s_cbranch_vccnz .LBB0_353
